# norm_rows<1> row loads as 16-byte global_load_dwordx4 (lane pairs exchange halves via v_cndmask_b32_dpp) + packed pass 2/3 + hand-written prologue converter
# speedup vs baseline: 1.0071x; 1.0034x over previous
; #define LAS __attribute__((address_space(3)))
; template <int MODE> ...
;     ...
;     LAS float* GP = (LAS float*)lds; LAS float* GN = (LAS float*)(lds + 16384); LAS float* GI = (LAS float*)(lds + 32768);
;     __syncthreads();
; #pragma unroll
;     for (int i = 0; i < 2; ++i) { const int o = 4 * (tid + NTHREADS * i);
;         if (MODE != 0) { *(LAS f32x4*)(GP + o) = *(const f32x4*)(gpost + o); const f32x4 g = *(const f32x4*)(gprev + o); *(LAS f32x4*)(GI + o) = (f32x4){1.f / g.x, 1.f / g.y, 1.f / g.z, 1.f / g.w}; }
;         if (MODE != 2) *(LAS f32x4*)(GN + o) = *(const f32x4*)(gpre + o); }
;     __syncthreads();
;     const int lo4 = 4 * lane;
.LBB0_772:
	s_cmp_gt_i32 s36, 6
	s_cselect_b64 s[6:7], -1, 0
	s_xor_b64 s[4:5], s[4:5], -1
	s_or_b64 s[4:5], s[6:7], s[4:5]
	s_and_b64 vcc, exec, s[4:5]
	s_cbranch_vccnz .LBB0_778
	s_mov_b64 s[12:13], 0
	v_mbcnt_lo_u32_b32 v2, -1, 0
	v_mbcnt_hi_u32_b32 v2, -1, v2
	s_load_dwordx4 s[4:7], s[0:1], 0x10
	s_load_dwordx2 s[8:9], s[0:1], 0x70
	v_lshlrev_b32_e32 v0, 2, v2
	v_lshl_add_u32 v24, s89, 8, v0
	v_ashrrev_i32_e32 v25, 31, v24
	v_lshlrev_b64 v[12:13], 2, v[24:25]
	v_add_u32_e32 v16, 0x800, v24
	s_waitcnt lgkmcnt(0)
	v_lshl_add_u64 v[8:9], s[4:5], 0, v[12:13]
	v_ashrrev_i32_e32 v17, 31, v16
	s_waitcnt vmcnt(0)
	s_barrier
	v_lshl_add_u64 v[4:5], s[6:7], 0, v[12:13]
	global_load_dwordx4 v[8:11], v[8:9], off
	v_lshl_add_u64 v[12:13], s[8:9], 0, v[12:13]
	v_lshlrev_b64 v[26:27], 2, v[16:17]
	global_load_dwordx4 v[4:7], v[4:5], off
	v_lshl_add_u64 v[16:17], s[6:7], 0, v[26:27]
	global_load_dwordx4 v[12:15], v[12:13], off
	v_lshl_add_u64 v[20:21], s[4:5], 0, v[26:27]
	global_load_dwordx4 v[16:19], v[16:17], off
	v_lshl_add_u32 v1, v24, 2, 0
	global_load_dwordx4 v[20:23], v[20:21], off
	v_lshl_add_u64 v[24:25], s[8:9], 0, v[26:27]
	global_load_dwordx4 v[24:27], v[24:25], off
	s_cmpk_gt_i32 s40, 0x1fff
	s_waitcnt vmcnt(5)
	v_div_scale_f32 v3, s[4:5], v8, v8, 1.0
	v_div_scale_f32 v29, s[8:9], v11, v11, 1.0
	s_waitcnt vmcnt(4)
	ds_write_b128 v1, v[4:7]
	v_div_scale_f32 v5, s[4:5], v9, v9, 1.0
	s_waitcnt vmcnt(3)
	ds_write_b128 v1, v[12:15] offset:16384
	v_rcp_f32_e32 v12, v3
	v_div_scale_f32 v7, s[6:7], v10, v10, 1.0
	v_rcp_f32_e32 v13, v5
	s_waitcnt vmcnt(2)
	ds_write_b128 v1, v[16:19] offset:8192
	s_waitcnt vmcnt(1)
	v_div_scale_f32 v16, s[10:11], v20, v20, 1.0
	v_rcp_f32_e32 v14, v7
	v_rcp_f32_e32 v19, v16
	v_rcp_f32_e32 v15, v29
	v_fma_f32 v32, -v3, v12, 1.0
	v_div_scale_f32 v4, vcc, 1.0, v8, 1.0
	v_fma_f32 v33, -v5, v13, 1.0
	v_fmac_f32_e32 v12, v32, v12
	v_div_scale_f32 v6, s[4:5], 1.0, v9, 1.0
	v_fma_f32 v34, -v7, v14, 1.0
	v_fmac_f32_e32 v13, v33, v13
	v_fma_f32 v32, -v16, v19, 1.0
	v_mul_f32_e32 v33, v4, v12
	v_div_scale_f32 v28, s[6:7], 1.0, v10, 1.0
	v_fma_f32 v35, -v29, v15, 1.0
	v_fmac_f32_e32 v14, v34, v14
	v_mul_f32_e32 v34, v6, v13
	v_fmac_f32_e32 v19, v32, v19
	v_fma_f32 v32, -v3, v33, v4
	v_div_scale_f32 v30, s[8:9], 1.0, v11, 1.0
	v_fmac_f32_e32 v15, v35, v15
	v_mul_f32_e32 v35, v28, v14
	v_fma_f32 v37, -v5, v34, v6
	v_fmac_f32_e32 v33, v32, v12
	v_div_scale_f32 v17, s[10:11], 1.0, v20, 1.0
	v_mul_f32_e32 v36, v30, v15
	v_fma_f32 v38, -v7, v35, v28
	v_fmac_f32_e32 v34, v37, v13
	v_fma_f32 v3, -v3, v33, v4
	v_div_scale_f32 v18, s[14:15], v21, v21, 1.0
	v_fma_f32 v39, -v29, v36, v30
	v_mul_f32_e32 v40, v17, v19
	v_fmac_f32_e32 v35, v38, v14
	v_fma_f32 v5, -v5, v34, v6
	v_div_fmas_f32 v3, v3, v12, v33
	s_mov_b64 vcc, s[4:5]
	v_rcp_f32_e32 v31, v18
	v_fmac_f32_e32 v36, v39, v15
	v_fma_f32 v32, -v16, v40, v17
	v_fma_f32 v6, -v7, v35, v28
	v_div_fixup_f32 v4, v3, v8, 1.0
	v_div_fmas_f32 v3, v5, v13, v34
	s_mov_b64 vcc, s[6:7]
	v_fma_f32 v7, -v29, v36, v30
	v_fmac_f32_e32 v40, v32, v19
	v_div_fixup_f32 v5, v3, v9, 1.0
	v_div_fmas_f32 v3, v6, v14, v35
	s_mov_b64 vcc, s[8:9]
	v_fma_f32 v12, -v16, v40, v17
	v_div_fixup_f32 v6, v3, v10, 1.0
	v_div_fmas_f32 v3, v7, v15, v36
	s_mov_b64 vcc, s[10:11]
	v_div_fixup_f32 v7, v3, v11, 1.0
	v_div_fmas_f32 v3, v12, v19, v40
	ds_write_b128 v1, v[4:7] offset:32768
	v_div_fixup_f32 v4, v3, v20, 1.0
	v_fma_f32 v3, -v18, v31, 1.0
	v_fmac_f32_e32 v31, v3, v31
	v_div_scale_f32 v3, vcc, 1.0, v21, 1.0
	v_mul_f32_e32 v5, v3, v31
	v_fma_f32 v6, -v18, v5, v3
	v_fmac_f32_e32 v5, v6, v31
	v_div_scale_f32 v6, s[4:5], v22, v22, 1.0
	v_rcp_f32_e32 v7, v6
	v_fma_f32 v3, -v18, v5, v3
	v_div_fmas_f32 v3, v3, v31, v5
	v_div_fixup_f32 v5, v3, v21, 1.0
	v_fma_f32 v3, -v6, v7, 1.0
	v_fmac_f32_e32 v7, v3, v7
	v_div_scale_f32 v3, vcc, 1.0, v22, 1.0
	v_mul_f32_e32 v8, v3, v7
	v_fma_f32 v9, -v6, v8, v3
	v_fmac_f32_e32 v8, v9, v7
	v_div_scale_f32 v9, s[4:5], v23, v23, 1.0
	v_rcp_f32_e32 v10, v9
	v_fma_f32 v3, -v6, v8, v3
	v_div_fmas_f32 v3, v3, v7, v8
	v_div_fixup_f32 v6, v3, v22, 1.0
	v_fma_f32 v3, -v9, v10, 1.0
	v_fmac_f32_e32 v10, v3, v10
	v_div_scale_f32 v3, vcc, 1.0, v23, 1.0
	v_mul_f32_e32 v7, v3, v10
	v_fma_f32 v8, -v9, v7, v3
	v_fmac_f32_e32 v7, v8, v10
	v_fma_f32 v3, -v9, v7, v3
	v_div_fmas_f32 v3, v3, v10, v7
	v_div_fixup_f32 v7, v3, v23, 1.0
	ds_write_b128 v1, v[4:7] offset:40960
	s_waitcnt vmcnt(0)
	ds_write_b128 v1, v[24:27] offset:24576
	s_waitcnt lgkmcnt(0)
	s_barrier
	s_cbranch_scc1 .LBB0_778
	s_load_dwordx2 s[6:7], s[0:1], 0xe8
	s_ashr_i32 s41, s40, 31
	s_lshl_b64 s[8:9], s[40:41], 2
	v_ashrrev_i32_e32 v1, 31, v0
	v_cmp_eq_u32_e64 s[4:5], 0, v2
	s_waitcnt lgkmcnt(0)
	s_add_u32 s8, s6, s8
	s_addc_u32 s9, s7, s9
	s_add_u32 s64, s8, 0x2c0000
	s_addc_u32 s65, s9, 0
	s_ashr_i32 s39, s38, 31
	s_lshl_b64 s[8:9], s[38:39], 2
	s_lshl_b64 s[10:11], s[40:41], 13
	s_add_u32 s6, s6, s10
	s_addc_u32 s7, s7, s11
	v_mbcnt_lo_u32_b32 v2, -1, 0
	v_lshl_add_u32 v71, v0, 2, 0
	v_lshl_add_u64 v[0:1], v[0:1], 1, s[6:7]
	s_lshl_b64 s[10:11], s[38:39], 13
	s_mov_b64 s[14:15], 0x3000000
	s_mov_b64 s[18:19], 0x3000200
	s_mov_b64 s[20:21], 0x3000400
	s_mov_b64 s[22:23], 0x3000600
	s_mov_b64 s[24:25], 0x3000800
	s_mov_b64 s[26:27], 0x3000a00
	s_mov_b64 s[42:43], 0x3000c00
	s_mov_b64 s[44:45], 0x3000e00
	s_mov_b64 s[46:47], 0x3001000
	s_mov_b32 s39, 0x3001000
	s_mov_b32 s41, 0x7001000
	s_mov_b64 s[48:49], 0x3001200
	s_mov_b64 s[50:51], 0x3001400
	s_mov_b64 s[52:53], 0x3001600
	s_mov_b64 s[54:55], 0x3001800
	s_mov_b64 s[56:57], 0x3001a00
	s_mov_b64 s[58:59], 0x3001c00
	s_mov_b64 s[60:61], 0x3001e00
	v_mov_b32_e32 v98, 0
	v_mov_b32_e32 v99, 0x358637bd
	s_mov_b32 s66, 0x800000
	v_mbcnt_hi_u32_b32 v100, -1, v2
	s_mov_b32 s67, s40
	s_mov_b32 s96, 0x3000000
	s_mov_b32 s97, 0x3001000
	v_mbcnt_lo_u32_b32 v236, -1, 0
	v_mbcnt_hi_u32_b32 v236, -1, v236
	v_and_b32_e32 v236, 1, v236
	v_mul_u32_u24_e32 v236, 0x1f8, v236
	s_branch .LBB0_776

; template <int MODE> ...
;     ...
;             const bf16* pr = xn + (size_t)row * DM; bf16* pw_out = xn_out + (size_t)row * DM; const bf16* hr = hb + (size_t)row * DM;
;             v2u pw[16], hw[16]; float ss = 0.f;
; #pragma unroll
;             for (int j = 0; j < 16; ++j) { pw[j] = *(const v2u*)(pr + lo4 + 256 * j); hw[j] = *(const v2u*)(hr + lo4 + 256 * j); }
.LBB0_776:
	v_lshl_add_u64 v[66:67], v[0:1], 0, s[12:13]
	s_add_u32 s62, s64, s12
	s_addc_u32 s63, s65, s13
	global_load_dword v78, v98, s[62:63]
	v_add_co_u32_e32 v196, vcc, v236, v66
	s_nop 1
	v_addc_co_u32_e32 v197, vcc, 0, v67, vcc
	v_add_co_u32_e32 v198, vcc, 0x7000000, v196
	s_nop 1
	v_addc_co_u32_e32 v199, vcc, 0, v197, vcc
	v_add_co_u32_e32 v200, vcc, 0x7001000, v196
	s_nop 1
	v_addc_co_u32_e32 v201, vcc, 0, v197, vcc
	v_add_co_u32_e32 v202, vcc, 0x3000000, v196
	s_nop 1
	v_addc_co_u32_e32 v203, vcc, 0, v197, vcc
	v_add_co_u32_e32 v204, vcc, 0x3001000, v196
	s_nop 1
	v_addc_co_u32_e32 v205, vcc, 0, v197, vcc
	global_load_dwordx4 v[132:135], v[198:199], off
	global_load_dwordx4 v[136:139], v[198:199], off offset:1024
	global_load_dwordx4 v[140:143], v[198:199], off offset:2048
	global_load_dwordx4 v[144:147], v[198:199], off offset:3072
	global_load_dwordx4 v[148:151], v[200:201], off
	global_load_dwordx4 v[152:155], v[200:201], off offset:1024
	global_load_dwordx4 v[156:159], v[200:201], off offset:2048
	global_load_dwordx4 v[160:163], v[200:201], off offset:3072
	global_load_dwordx4 v[164:167], v[202:203], off
	global_load_dwordx4 v[168:171], v[202:203], off offset:1024
	global_load_dwordx4 v[172:175], v[202:203], off offset:2048
	global_load_dwordx4 v[176:179], v[202:203], off offset:3072
	global_load_dwordx4 v[180:183], v[204:205], off
	global_load_dwordx4 v[184:187], v[204:205], off offset:1024
	global_load_dwordx4 v[188:191], v[204:205], off offset:2048
	global_load_dwordx4 v[192:195], v[204:205], off offset:3072
	s_waitcnt vmcnt(0)
	s_mov_b32 vcc_lo, 0x55555555
	s_mov_b32 vcc_hi, 0x55555555
	s_nop 1
	v_cndmask_b32_dpp v60, v134, v132, vcc quad_perm:[1,0,3,2] row_mask:0xf bank_mask:0xf
	v_cndmask_b32_dpp v61, v135, v133, vcc quad_perm:[1,0,3,2] row_mask:0xf bank_mask:0xf
	v_cndmask_b32_dpp v52, v138, v136, vcc quad_perm:[1,0,3,2] row_mask:0xf bank_mask:0xf
	v_cndmask_b32_dpp v53, v139, v137, vcc quad_perm:[1,0,3,2] row_mask:0xf bank_mask:0xf
	v_cndmask_b32_dpp v44, v142, v140, vcc quad_perm:[1,0,3,2] row_mask:0xf bank_mask:0xf
	v_cndmask_b32_dpp v45, v143, v141, vcc quad_perm:[1,0,3,2] row_mask:0xf bank_mask:0xf
	v_cndmask_b32_dpp v38, v146, v144, vcc quad_perm:[1,0,3,2] row_mask:0xf bank_mask:0xf
	v_cndmask_b32_dpp v39, v147, v145, vcc quad_perm:[1,0,3,2] row_mask:0xf bank_mask:0xf
	v_cndmask_b32_dpp v32, v150, v148, vcc quad_perm:[1,0,3,2] row_mask:0xf bank_mask:0xf
	v_cndmask_b32_dpp v33, v151, v149, vcc quad_perm:[1,0,3,2] row_mask:0xf bank_mask:0xf
	v_cndmask_b32_dpp v24, v154, v152, vcc quad_perm:[1,0,3,2] row_mask:0xf bank_mask:0xf
	v_cndmask_b32_dpp v25, v155, v153, vcc quad_perm:[1,0,3,2] row_mask:0xf bank_mask:0xf
	v_cndmask_b32_dpp v16, v158, v156, vcc quad_perm:[1,0,3,2] row_mask:0xf bank_mask:0xf
	v_cndmask_b32_dpp v17, v159, v157, vcc quad_perm:[1,0,3,2] row_mask:0xf bank_mask:0xf
	v_cndmask_b32_dpp v8, v162, v160, vcc quad_perm:[1,0,3,2] row_mask:0xf bank_mask:0xf
	v_cndmask_b32_dpp v9, v163, v161, vcc quad_perm:[1,0,3,2] row_mask:0xf bank_mask:0xf
	v_cndmask_b32_dpp v64, v166, v164, vcc quad_perm:[1,0,3,2] row_mask:0xf bank_mask:0xf
	v_cndmask_b32_dpp v65, v167, v165, vcc quad_perm:[1,0,3,2] row_mask:0xf bank_mask:0xf
	v_cndmask_b32_dpp v58, v170, v168, vcc quad_perm:[1,0,3,2] row_mask:0xf bank_mask:0xf
	v_cndmask_b32_dpp v59, v171, v169, vcc quad_perm:[1,0,3,2] row_mask:0xf bank_mask:0xf
	v_cndmask_b32_dpp v50, v174, v172, vcc quad_perm:[1,0,3,2] row_mask:0xf bank_mask:0xf
	v_cndmask_b32_dpp v51, v175, v173, vcc quad_perm:[1,0,3,2] row_mask:0xf bank_mask:0xf
	v_cndmask_b32_dpp v40, v178, v176, vcc quad_perm:[1,0,3,2] row_mask:0xf bank_mask:0xf
	v_cndmask_b32_dpp v41, v179, v177, vcc quad_perm:[1,0,3,2] row_mask:0xf bank_mask:0xf
	v_cndmask_b32_dpp v30, v182, v180, vcc quad_perm:[1,0,3,2] row_mask:0xf bank_mask:0xf
	v_cndmask_b32_dpp v31, v183, v181, vcc quad_perm:[1,0,3,2] row_mask:0xf bank_mask:0xf
	v_cndmask_b32_dpp v22, v186, v184, vcc quad_perm:[1,0,3,2] row_mask:0xf bank_mask:0xf
	v_cndmask_b32_dpp v23, v187, v185, vcc quad_perm:[1,0,3,2] row_mask:0xf bank_mask:0xf
	v_cndmask_b32_dpp v14, v190, v188, vcc quad_perm:[1,0,3,2] row_mask:0xf bank_mask:0xf
	v_cndmask_b32_dpp v15, v191, v189, vcc quad_perm:[1,0,3,2] row_mask:0xf bank_mask:0xf
	v_cndmask_b32_dpp v6, v194, v192, vcc quad_perm:[1,0,3,2] row_mask:0xf bank_mask:0xf
	v_cndmask_b32_dpp v7, v195, v193, vcc quad_perm:[1,0,3,2] row_mask:0xf bank_mask:0xf
	s_mov_b32 vcc_lo, 0xaaaaaaaa
	s_mov_b32 vcc_hi, 0xaaaaaaaa
	s_nop 1
	v_cndmask_b32_dpp v54, v132, v134, vcc quad_perm:[1,0,3,2] row_mask:0xf bank_mask:0xf
	v_cndmask_b32_dpp v55, v133, v135, vcc quad_perm:[1,0,3,2] row_mask:0xf bank_mask:0xf
	v_cndmask_b32_dpp v48, v136, v138, vcc quad_perm:[1,0,3,2] row_mask:0xf bank_mask:0xf
	v_cndmask_b32_dpp v49, v137, v139, vcc quad_perm:[1,0,3,2] row_mask:0xf bank_mask:0xf
	v_cndmask_b32_dpp v42, v140, v142, vcc quad_perm:[1,0,3,2] row_mask:0xf bank_mask:0xf
	v_cndmask_b32_dpp v43, v141, v143, vcc quad_perm:[1,0,3,2] row_mask:0xf bank_mask:0xf
	v_cndmask_b32_dpp v34, v144, v146, vcc quad_perm:[1,0,3,2] row_mask:0xf bank_mask:0xf
	v_cndmask_b32_dpp v35, v145, v147, vcc quad_perm:[1,0,3,2] row_mask:0xf bank_mask:0xf
	v_cndmask_b32_dpp v28, v148, v150, vcc quad_perm:[1,0,3,2] row_mask:0xf bank_mask:0xf
	v_cndmask_b32_dpp v29, v149, v151, vcc quad_perm:[1,0,3,2] row_mask:0xf bank_mask:0xf
	v_cndmask_b32_dpp v20, v152, v154, vcc quad_perm:[1,0,3,2] row_mask:0xf bank_mask:0xf
	v_cndmask_b32_dpp v21, v153, v155, vcc quad_perm:[1,0,3,2] row_mask:0xf bank_mask:0xf
	v_cndmask_b32_dpp v12, v156, v158, vcc quad_perm:[1,0,3,2] row_mask:0xf bank_mask:0xf
; __device__ __forceinline__ float bflo(unsigned w) { return __uint_as_float(w << 16); }
; __device__ __forceinline__ float bfhi(unsigned w) { return __uint_as_float(w & 0xffff0000u); }
; template <int MODE> ...
;     ...
;             for (int j = 0; j < 16; ++j) { pw[j] = *(const v2u*)(pr + lo4 + 256 * j); hw[j] = *(const v2u*)(hr + lo4 + 256 * j); }
;             const float ri = 1.f / rs[row];
; #pragma unroll
;             for (int j = 0; j < 16; ++j) { const float a = bflo(hw[j].x), b = bfhi(hw[j].x), c = bflo(hw[j].y), d = bfhi(hw[j].y); ss += a * a + b * b + c * c + d * d; }
	v_cndmask_b32_dpp v13, v157, v159, vcc quad_perm:[1,0,3,2] row_mask:0xf bank_mask:0xf
	v_cndmask_b32_dpp v4, v160, v162, vcc quad_perm:[1,0,3,2] row_mask:0xf bank_mask:0xf
	v_cndmask_b32_dpp v5, v161, v163, vcc quad_perm:[1,0,3,2] row_mask:0xf bank_mask:0xf
	v_cndmask_b32_dpp v62, v164, v166, vcc quad_perm:[1,0,3,2] row_mask:0xf bank_mask:0xf
	v_cndmask_b32_dpp v63, v165, v167, vcc quad_perm:[1,0,3,2] row_mask:0xf bank_mask:0xf
	v_cndmask_b32_dpp v56, v168, v170, vcc quad_perm:[1,0,3,2] row_mask:0xf bank_mask:0xf
	v_cndmask_b32_dpp v57, v169, v171, vcc quad_perm:[1,0,3,2] row_mask:0xf bank_mask:0xf
	v_cndmask_b32_dpp v46, v172, v174, vcc quad_perm:[1,0,3,2] row_mask:0xf bank_mask:0xf
	v_cndmask_b32_dpp v47, v173, v175, vcc quad_perm:[1,0,3,2] row_mask:0xf bank_mask:0xf
	v_cndmask_b32_dpp v36, v176, v178, vcc quad_perm:[1,0,3,2] row_mask:0xf bank_mask:0xf
	v_cndmask_b32_dpp v37, v177, v179, vcc quad_perm:[1,0,3,2] row_mask:0xf bank_mask:0xf
	v_cndmask_b32_dpp v26, v180, v182, vcc quad_perm:[1,0,3,2] row_mask:0xf bank_mask:0xf
	v_cndmask_b32_dpp v27, v181, v183, vcc quad_perm:[1,0,3,2] row_mask:0xf bank_mask:0xf
	v_cndmask_b32_dpp v18, v184, v186, vcc quad_perm:[1,0,3,2] row_mask:0xf bank_mask:0xf
	v_cndmask_b32_dpp v19, v185, v187, vcc quad_perm:[1,0,3,2] row_mask:0xf bank_mask:0xf
	v_cndmask_b32_dpp v10, v188, v190, vcc quad_perm:[1,0,3,2] row_mask:0xf bank_mask:0xf
	v_cndmask_b32_dpp v11, v189, v191, vcc quad_perm:[1,0,3,2] row_mask:0xf bank_mask:0xf
	v_cndmask_b32_dpp v2, v192, v194, vcc quad_perm:[1,0,3,2] row_mask:0xf bank_mask:0xf
	v_cndmask_b32_dpp v3, v193, v195, vcc quad_perm:[1,0,3,2] row_mask:0xf bank_mask:0xf
	v_and_b32_e32 v69, 0xffff0000, v60
	s_waitcnt vmcnt(31)
	v_and_b32_e32 v74, 0xffff0000, v54
	v_lshlrev_b32_e32 v68, 16, v60
	v_lshlrev_b32_e32 v73, 16, v54
	v_mul_f32_e32 v69, v69, v69
	v_mul_f32_e32 v74, v74, v74
	v_lshlrev_b32_e32 v70, 16, v61
	v_lshlrev_b32_e32 v75, 16, v55
	s_waitcnt vmcnt(30)
	v_and_b32_e32 v79, 0xffff0000, v52
	v_fmac_f32_e32 v69, v68, v68
	v_fmac_f32_e32 v74, v73, v73
	v_and_b32_e32 v72, 0xffff0000, v61
	v_and_b32_e32 v76, 0xffff0000, v55
	v_lshlrev_b32_e32 v77, 16, v52
	s_waitcnt vmcnt(29)
	v_and_b32_e32 v83, 0xffff0000, v48
	s_waitcnt vmcnt(28)
	v_and_b32_e32 v87, 0xffff0000, v44
	v_mul_f32_e32 v79, v79, v79
	v_fmac_f32_e32 v69, v70, v70
	v_fmac_f32_e32 v74, v75, v75
	v_lshlrev_b32_e32 v80, 16, v53
	v_lshlrev_b32_e32 v82, 16, v48
	v_lshlrev_b32_e32 v86, 16, v44
	v_mul_f32_e32 v83, v83, v83
	v_fmac_f32_e32 v79, v77, v77
	v_fmac_f32_e32 v69, v72, v72
	v_fmac_f32_e32 v74, v76, v76
	v_mul_f32_e32 v72, v87, v87
	v_and_b32_e32 v81, 0xffff0000, v53
	v_lshlrev_b32_e32 v84, 16, v49
	v_fmac_f32_e32 v83, v82, v82
	v_fmac_f32_e32 v79, v80, v80
	v_add_f32_e32 v68, v69, v74
	v_lshlrev_b32_e32 v69, 16, v45
	v_fmac_f32_e32 v72, v86, v86
	v_and_b32_e32 v85, 0xffff0000, v49
	v_fmac_f32_e32 v83, v84, v84
	v_fmac_f32_e32 v79, v81, v81
	v_and_b32_e32 v70, 0xffff0000, v45
	v_fmac_f32_e32 v72, v69, v69
	v_fmac_f32_e32 v83, v85, v85
	v_add_f32_e32 v68, v68, v79
	v_fmac_f32_e32 v72, v70, v70
	s_waitcnt vmcnt(27)
	v_and_b32_e32 v70, 0xffff0000, v42
	v_add_f32_e32 v68, v68, v83
	v_lshlrev_b32_e32 v69, 16, v42
	v_mul_f32_e32 v70, v70, v70
	v_add_f32_e32 v68, v68, v72
	v_lshlrev_b32_e32 v72, 16, v43
	v_fmac_f32_e32 v70, v69, v69
	v_and_b32_e32 v73, 0xffff0000, v43
	v_fmac_f32_e32 v70, v72, v72
	v_fmac_f32_e32 v70, v73, v73
	v_add_f32_e32 v68, v68, v70
	s_waitcnt vmcnt(26)
	v_and_b32_e32 v70, 0xffff0000, v38
	v_lshlrev_b32_e32 v69, 16, v38
	v_mul_f32_e32 v70, v70, v70
	v_lshlrev_b32_e32 v72, 16, v39
	v_fmac_f32_e32 v70, v69, v69
	v_and_b32_e32 v73, 0xffff0000, v39
	v_fmac_f32_e32 v70, v72, v72
	v_fmac_f32_e32 v70, v73, v73
	v_add_f32_e32 v68, v68, v70
	s_waitcnt vmcnt(17)
	v_and_b32_e32 v70, 0xffff0000, v34
	v_lshlrev_b32_e32 v69, 16, v34
	v_mul_f32_e32 v70, v70, v70
	v_lshlrev_b32_e32 v72, 16, v35
	v_fmac_f32_e32 v70, v69, v69
	v_and_b32_e32 v73, 0xffff0000, v35
	v_fmac_f32_e32 v70, v72, v72
	v_fmac_f32_e32 v70, v73, v73
	v_add_f32_e32 v68, v68, v70
	v_and_b32_e32 v70, 0xffff0000, v32
	v_lshlrev_b32_e32 v69, 16, v32
	v_mul_f32_e32 v70, v70, v70
	v_lshlrev_b32_e32 v72, 16, v33
	v_fmac_f32_e32 v70, v69, v69
	v_and_b32_e32 v73, 0xffff0000, v33
	v_fmac_f32_e32 v70, v72, v72
	v_fmac_f32_e32 v70, v73, v73
	v_add_f32_e32 v68, v68, v70
	v_and_b32_e32 v70, 0xffff0000, v28
	v_lshlrev_b32_e32 v69, 16, v28
	v_mul_f32_e32 v70, v70, v70
	v_lshlrev_b32_e32 v72, 16, v29
	v_fmac_f32_e32 v70, v69, v69
	v_and_b32_e32 v73, 0xffff0000, v29
	v_fmac_f32_e32 v70, v72, v72
	v_fmac_f32_e32 v70, v73, v73
	v_add_f32_e32 v68, v68, v70
	v_and_b32_e32 v70, 0xffff0000, v24
	v_lshlrev_b32_e32 v69, 16, v24
	v_mul_f32_e32 v70, v70, v70
	v_lshlrev_b32_e32 v72, 16, v25
	v_fmac_f32_e32 v70, v69, v69
	v_and_b32_e32 v73, 0xffff0000, v25
	v_fmac_f32_e32 v70, v72, v72
	v_fmac_f32_e32 v70, v73, v73
	v_add_f32_e32 v68, v68, v70
	v_and_b32_e32 v70, 0xffff0000, v20
	v_lshlrev_b32_e32 v69, 16, v20
	v_mul_f32_e32 v70, v70, v70
	v_lshlrev_b32_e32 v72, 16, v21
	v_fmac_f32_e32 v70, v69, v69
	v_and_b32_e32 v73, 0xffff0000, v21
	v_fmac_f32_e32 v70, v72, v72
	v_fmac_f32_e32 v70, v73, v73
	s_waitcnt vmcnt(11)
	v_and_b32_e32 v73, 0xffff0000, v12
	v_and_b32_e32 v72, 0xffff0000, v16
	v_add_f32_e32 v70, v68, v70
	v_lshlrev_b32_e32 v69, 16, v12
	v_lshlrev_b32_e32 v68, 16, v16
	v_pk_mul_f32 v[72:73], v[72:73], v[72:73]
	v_lshlrev_b32_e32 v75, 16, v13
	v_lshlrev_b32_e32 v74, 16, v17
	v_pk_fma_f32 v[68:69], v[68:69], v[68:69], v[72:73]
	v_and_b32_e32 v77, 0xffff0000, v13
	v_and_b32_e32 v76, 0xffff0000, v17
	v_pk_fma_f32 v[68:69], v[74:75], v[74:75], v[68:69]
	s_waitcnt vmcnt(9)
; #define LAS __attribute__((address_space(3)))
; __device__ __forceinline__ float bflo(unsigned w) { return __uint_as_float(w << 16); }
; __device__ __forceinline__ float bfhi(unsigned w) { return __uint_as_float(w & 0xffff0000u); }
; #define LAUNDER_ROW(pw, hw) do { LAUNDER8(pw, 0); LAUNDER8(pw, 8); LAUNDER8(hw, 0); LAUNDER8(hw, 8); } while (0)
; template <int MODE> ...
;     ...
;             const float ri = 1.f / rs[row];
; #pragma unroll
;             for (int j = 0; j < 16; ++j) { const float a = bflo(hw[j].x), b = bfhi(hw[j].x), c = bflo(hw[j].y), d = bfhi(hw[j].y); ss += a * a + b * b + c * c + d * d; }
;             const float rstd = rsqrtf(wave_sum(ss) * (1.f / DM) + EPS);
;             asm volatile("" ::: "memory");
;             LAUNDER_ROW(pw, hw);
;             float ss2 = 0.f;
; #pragma unroll
;             for (int j = 0; j < 16; ++j) { const f32x4 g = *(const LAS f32x4*)(GP + lo4 + 256 * j), gi = *(const LAS f32x4*)(GI + lo4 + 256 * j);
;                 f32x4 x;
;                 x.x = bflo(pw[j].x) * ri * gi.x + bflo(hw[j].x) * rstd * g.x; x.y = bfhi(pw[j].x) * ri * gi.y + bfhi(hw[j].x) * rstd * g.y;
;                 x.z = bflo(pw[j].y) * ri * gi.z + bflo(hw[j].y) * rstd * g.z; x.w = bfhi(pw[j].y) * ri * gi.w + bfhi(hw[j].y) * rstd * g.w;
;                 if (MODE == 2) *(f32x4*)(xout + (size_t)row * DM + lo4 + 256 * j) = x;
;                 else ss2 += x.x * x.x + x.y * x.y + x.z * x.z + x.w * x.w;
	v_and_b32_e32 v73, 0xffff0000, v4
	v_pk_fma_f32 v[68:69], v[76:77], v[76:77], v[68:69]
	v_and_b32_e32 v72, 0xffff0000, v8
	v_add_f32_e32 v68, v70, v68
	v_add_f32_e32 v70, v68, v69
	v_lshlrev_b32_e32 v69, 16, v4
	v_lshlrev_b32_e32 v68, 16, v8
	v_pk_mul_f32 v[72:73], v[72:73], v[72:73]
	v_lshlrev_b32_e32 v75, 16, v5
	v_lshlrev_b32_e32 v74, 16, v9
	v_pk_fma_f32 v[68:69], v[68:69], v[68:69], v[72:73]
	v_and_b32_e32 v77, 0xffff0000, v5
	v_and_b32_e32 v76, 0xffff0000, v9
	v_pk_fma_f32 v[68:69], v[74:75], v[74:75], v[68:69]
	s_waitcnt vmcnt(0)
	v_pk_fma_f32 v[68:69], v[76:77], v[76:77], v[68:69]
	v_div_scale_f32 v77, s[6:7], v78, v78, 1.0
	v_add_f32_e32 v68, v70, v68
	v_add_f32_e32 v68, v68, v69
	v_and_b32_e32 v69, 64, v100
	v_add_u32_e32 v69, 64, v69
	v_xor_b32_e32 v70, 1, v100
	v_cmp_lt_i32_e32 vcc, v70, v69
	v_rcp_f32_e32 v79, v77
	v_lshlrev_b32_e32 v86, 16, v60
	v_cndmask_b32_e32 v70, v100, v70, vcc
	v_lshlrev_b32_e32 v70, 2, v70
	ds_bpermute_b32 v72, v70, v68
	v_fma_f32 v80, -v77, v79, 1.0
	v_fmac_f32_e32 v79, v80, v79
	s_waitcnt lgkmcnt(0)
	v_add_f32_e32 v68, v68, v72
	v_xor_b32_e32 v72, 2, v100
	v_cmp_lt_i32_e32 vcc, v72, v69
	s_nop 1
	v_cndmask_b32_e32 v72, v100, v72, vcc
	v_lshlrev_b32_e32 v72, 2, v72
	ds_bpermute_b32 v73, v72, v68
	s_waitcnt lgkmcnt(0)
	v_add_f32_e32 v68, v68, v73
	v_xor_b32_e32 v73, 4, v100
	v_cmp_lt_i32_e32 vcc, v73, v69
	s_nop 1
	v_cndmask_b32_e32 v73, v100, v73, vcc
	v_lshlrev_b32_e32 v73, 2, v73
	ds_bpermute_b32 v74, v73, v68
	s_waitcnt lgkmcnt(0)
	v_add_f32_e32 v68, v68, v74
	v_xor_b32_e32 v74, 8, v100
	v_cmp_lt_i32_e32 vcc, v74, v69
	s_nop 1
	v_cndmask_b32_e32 v74, v100, v74, vcc
	v_lshlrev_b32_e32 v74, 2, v74
	ds_bpermute_b32 v75, v74, v68
	s_waitcnt lgkmcnt(0)
	v_add_f32_e32 v68, v68, v75
	v_xor_b32_e32 v75, 16, v100
	v_cmp_lt_i32_e32 vcc, v75, v69
	s_nop 1
	v_cndmask_b32_e32 v75, v100, v75, vcc
	v_lshlrev_b32_e32 v75, 2, v75
	ds_bpermute_b32 v76, v75, v68
	v_div_scale_f32 v80, vcc, 1.0, v78, 1.0
	v_mul_f32_e32 v81, v80, v79
	v_fma_f32 v82, -v77, v81, v80
	s_waitcnt lgkmcnt(0)
	v_add_f32_e32 v68, v68, v76
	v_xor_b32_e32 v76, 32, v100
	v_cmp_lt_i32_e64 s[6:7], v76, v69
	v_fmac_f32_e32 v81, v82, v79
	v_fma_f32 v77, -v77, v81, v80
	v_cndmask_b32_e64 v69, v100, v76, s[6:7]
	v_lshlrev_b32_e32 v76, 2, v69
	ds_bpermute_b32 v69, v76, v68
	s_waitcnt lgkmcnt(0)
	v_add_f32_e32 v68, v68, v69
	v_fmamk_f32 v68, v68, 0x39800000, v99
	v_mul_f32_e32 v69, 0x4b800000, v68
	v_cmp_gt_f32_e64 s[6:7], s66, v68
	s_nop 1
	v_cndmask_b32_e64 v68, v68, v69, s[6:7]
	v_rsq_f32_e32 v69, v68
	v_div_fmas_f32 v68, v77, v79, v81
	v_div_fixup_f32 v68, v68, v78, 1.0
	v_mul_f32_e32 v77, 0x45800000, v69
	v_cndmask_b32_e64 v69, v69, v77, s[6:7]
	v_mov_b32_e32 v228, v68
	v_mov_b32_e32 v229, v68
	v_mov_b32_e32 v230, v69
	v_mov_b32_e32 v231, v69
	ds_read_b128 v[196:199], v71
	ds_read_b128 v[200:203], v71 offset:32768
	ds_read_b128 v[204:207], v71 offset:1024
	ds_read_b128 v[208:211], v71 offset:33792
	v_lshlrev_b32_e32 v212, 16, v64
	v_and_b32_e32 v213, 0xffff0000, v64
	v_lshlrev_b32_e32 v214, 16, v65
	v_and_b32_e32 v215, 0xffff0000, v65
	v_lshlrev_b32_e32 v216, 16, v60
	v_and_b32_e32 v217, 0xffff0000, v60
	v_lshlrev_b32_e32 v218, 16, v61
	v_and_b32_e32 v219, 0xffff0000, v61
	v_pk_mul_f32 v[212:213], v[228:229], v[212:213]
	v_pk_mul_f32 v[214:215], v[228:229], v[214:215]
	v_pk_mul_f32 v[216:217], v[230:231], v[216:217]
	v_pk_mul_f32 v[218:219], v[230:231], v[218:219]
	s_waitcnt lgkmcnt(2)
	v_pk_mul_f32 v[132:133], v[212:213], v[200:201]
	v_pk_mul_f32 v[134:135], v[214:215], v[202:203]
	v_pk_fma_f32 v[132:133], v[196:197], v[216:217], v[132:133]
	v_pk_fma_f32 v[134:135], v[198:199], v[218:219], v[134:135]
	v_pk_mul_f32 v[234:235], v[132:133], v[132:133]
	v_pk_fma_f32 v[234:235], v[134:135], v[134:135], v[234:235]
	ds_read_b128 v[196:199], v71 offset:2048
	ds_read_b128 v[200:203], v71 offset:34816
	v_lshlrev_b32_e32 v212, 16, v62
	v_and_b32_e32 v213, 0xffff0000, v62
	v_lshlrev_b32_e32 v214, 16, v63
	v_and_b32_e32 v215, 0xffff0000, v63
	v_lshlrev_b32_e32 v216, 16, v54
	v_and_b32_e32 v217, 0xffff0000, v54
	v_lshlrev_b32_e32 v218, 16, v55
	v_and_b32_e32 v219, 0xffff0000, v55
	v_pk_mul_f32 v[212:213], v[228:229], v[212:213]
	v_pk_mul_f32 v[214:215], v[228:229], v[214:215]
	v_pk_mul_f32 v[216:217], v[230:231], v[216:217]
	v_pk_mul_f32 v[218:219], v[230:231], v[218:219]
	s_waitcnt lgkmcnt(2)
	v_pk_mul_f32 v[136:137], v[212:213], v[208:209]
	v_pk_mul_f32 v[138:139], v[214:215], v[210:211]
	v_pk_fma_f32 v[136:137], v[204:205], v[216:217], v[136:137]
	v_pk_fma_f32 v[138:139], v[206:207], v[218:219], v[138:139]
	v_pk_fma_f32 v[234:235], v[136:137], v[136:137], v[234:235]
	v_pk_fma_f32 v[234:235], v[138:139], v[138:139], v[234:235]
	ds_read_b128 v[204:207], v71 offset:3072
	ds_read_b128 v[208:211], v71 offset:35840
	v_lshlrev_b32_e32 v212, 16, v58
	v_and_b32_e32 v213, 0xffff0000, v58
	v_lshlrev_b32_e32 v214, 16, v59
	v_and_b32_e32 v215, 0xffff0000, v59
	v_lshlrev_b32_e32 v216, 16, v52
	v_and_b32_e32 v217, 0xffff0000, v52
	v_lshlrev_b32_e32 v218, 16, v53
	v_and_b32_e32 v219, 0xffff0000, v53
	v_pk_mul_f32 v[212:213], v[228:229], v[212:213]
	v_pk_mul_f32 v[214:215], v[228:229], v[214:215]
	v_pk_mul_f32 v[216:217], v[230:231], v[216:217]
	v_pk_mul_f32 v[218:219], v[230:231], v[218:219]
	s_waitcnt lgkmcnt(2)
; #define LAS __attribute__((address_space(3)))
; __device__ __forceinline__ float bflo(unsigned w) { return __uint_as_float(w << 16); }
; __device__ __forceinline__ float bfhi(unsigned w) { return __uint_as_float(w & 0xffff0000u); }
; template <int MODE> ...
;     ...
; #pragma unroll
;             for (int j = 0; j < 16; ++j) { const f32x4 g = *(const LAS f32x4*)(GP + lo4 + 256 * j), gi = *(const LAS f32x4*)(GI + lo4 + 256 * j);
;                 f32x4 x;
;                 x.x = bflo(pw[j].x) * ri * gi.x + bflo(hw[j].x) * rstd * g.x; x.y = bfhi(pw[j].x) * ri * gi.y + bfhi(hw[j].x) * rstd * g.y;
;                 x.z = bflo(pw[j].y) * ri * gi.z + bflo(hw[j].y) * rstd * g.z; x.w = bfhi(pw[j].y) * ri * gi.w + bfhi(hw[j].y) * rstd * g.w;
;                 if (MODE == 2) *(f32x4*)(xout + (size_t)row * DM + lo4 + 256 * j) = x;
;                 else ss2 += x.x * x.x + x.y * x.y + x.z * x.z + x.w * x.w;
;                 if (j & 1) __builtin_amdgcn_sched_barrier(0); }
	v_pk_mul_f32 v[140:141], v[212:213], v[200:201]
	v_pk_mul_f32 v[142:143], v[214:215], v[202:203]
	v_pk_fma_f32 v[140:141], v[196:197], v[216:217], v[140:141]
	v_pk_fma_f32 v[142:143], v[198:199], v[218:219], v[142:143]
	v_pk_fma_f32 v[234:235], v[140:141], v[140:141], v[234:235]
	v_pk_fma_f32 v[234:235], v[142:143], v[142:143], v[234:235]
	ds_read_b128 v[196:199], v71 offset:4096
	ds_read_b128 v[200:203], v71 offset:36864
	v_lshlrev_b32_e32 v212, 16, v56
	v_and_b32_e32 v213, 0xffff0000, v56
	v_lshlrev_b32_e32 v214, 16, v57
	v_and_b32_e32 v215, 0xffff0000, v57
	v_lshlrev_b32_e32 v216, 16, v48
	v_and_b32_e32 v217, 0xffff0000, v48
	v_lshlrev_b32_e32 v218, 16, v49
	v_and_b32_e32 v219, 0xffff0000, v49
	v_pk_mul_f32 v[212:213], v[228:229], v[212:213]
	v_pk_mul_f32 v[214:215], v[228:229], v[214:215]
	v_pk_mul_f32 v[216:217], v[230:231], v[216:217]
	v_pk_mul_f32 v[218:219], v[230:231], v[218:219]
	s_waitcnt lgkmcnt(2)
	v_pk_mul_f32 v[144:145], v[212:213], v[208:209]
	v_pk_mul_f32 v[146:147], v[214:215], v[210:211]
	v_pk_fma_f32 v[144:145], v[204:205], v[216:217], v[144:145]
	v_pk_fma_f32 v[146:147], v[206:207], v[218:219], v[146:147]
	v_pk_fma_f32 v[234:235], v[144:145], v[144:145], v[234:235]
	v_pk_fma_f32 v[234:235], v[146:147], v[146:147], v[234:235]
	ds_read_b128 v[204:207], v71 offset:5120
	ds_read_b128 v[208:211], v71 offset:37888
	v_lshlrev_b32_e32 v212, 16, v50
	v_and_b32_e32 v213, 0xffff0000, v50
	v_lshlrev_b32_e32 v214, 16, v51
	v_and_b32_e32 v215, 0xffff0000, v51
	v_lshlrev_b32_e32 v216, 16, v44
	v_and_b32_e32 v217, 0xffff0000, v44
	v_lshlrev_b32_e32 v218, 16, v45
	v_and_b32_e32 v219, 0xffff0000, v45
	v_pk_mul_f32 v[212:213], v[228:229], v[212:213]
	v_pk_mul_f32 v[214:215], v[228:229], v[214:215]
	v_pk_mul_f32 v[216:217], v[230:231], v[216:217]
	v_pk_mul_f32 v[218:219], v[230:231], v[218:219]
	s_waitcnt lgkmcnt(2)
	v_pk_mul_f32 v[148:149], v[212:213], v[200:201]
	v_pk_mul_f32 v[150:151], v[214:215], v[202:203]
	v_pk_fma_f32 v[148:149], v[196:197], v[216:217], v[148:149]
	v_pk_fma_f32 v[150:151], v[198:199], v[218:219], v[150:151]
	v_pk_fma_f32 v[234:235], v[148:149], v[148:149], v[234:235]
	v_pk_fma_f32 v[234:235], v[150:151], v[150:151], v[234:235]
	ds_read_b128 v[196:199], v71 offset:6144
	ds_read_b128 v[200:203], v71 offset:38912
	v_lshlrev_b32_e32 v212, 16, v46
	v_and_b32_e32 v213, 0xffff0000, v46
	v_lshlrev_b32_e32 v214, 16, v47
	v_and_b32_e32 v215, 0xffff0000, v47
	v_lshlrev_b32_e32 v216, 16, v42
	v_and_b32_e32 v217, 0xffff0000, v42
	v_lshlrev_b32_e32 v218, 16, v43
	v_and_b32_e32 v219, 0xffff0000, v43
	v_pk_mul_f32 v[212:213], v[228:229], v[212:213]
	v_pk_mul_f32 v[214:215], v[228:229], v[214:215]
	v_pk_mul_f32 v[216:217], v[230:231], v[216:217]
	v_pk_mul_f32 v[218:219], v[230:231], v[218:219]
	s_waitcnt lgkmcnt(2)
	v_pk_mul_f32 v[152:153], v[212:213], v[208:209]
	v_pk_mul_f32 v[154:155], v[214:215], v[210:211]
	v_pk_fma_f32 v[152:153], v[204:205], v[216:217], v[152:153]
	v_pk_fma_f32 v[154:155], v[206:207], v[218:219], v[154:155]
	v_pk_fma_f32 v[234:235], v[152:153], v[152:153], v[234:235]
	v_pk_fma_f32 v[234:235], v[154:155], v[154:155], v[234:235]
	ds_read_b128 v[204:207], v71 offset:7168
	ds_read_b128 v[208:211], v71 offset:39936
	v_lshlrev_b32_e32 v212, 16, v40
	v_and_b32_e32 v213, 0xffff0000, v40
	v_lshlrev_b32_e32 v214, 16, v41
	v_and_b32_e32 v215, 0xffff0000, v41
	v_lshlrev_b32_e32 v216, 16, v38
	v_and_b32_e32 v217, 0xffff0000, v38
	v_lshlrev_b32_e32 v218, 16, v39
	v_and_b32_e32 v219, 0xffff0000, v39
	v_pk_mul_f32 v[212:213], v[228:229], v[212:213]
	v_pk_mul_f32 v[214:215], v[228:229], v[214:215]
	v_pk_mul_f32 v[216:217], v[230:231], v[216:217]
	v_pk_mul_f32 v[218:219], v[230:231], v[218:219]
	s_waitcnt lgkmcnt(2)
	v_pk_mul_f32 v[156:157], v[212:213], v[200:201]
	v_pk_mul_f32 v[158:159], v[214:215], v[202:203]
	v_pk_fma_f32 v[156:157], v[196:197], v[216:217], v[156:157]
	v_pk_fma_f32 v[158:159], v[198:199], v[218:219], v[158:159]
	v_pk_fma_f32 v[234:235], v[156:157], v[156:157], v[234:235]
	v_pk_fma_f32 v[234:235], v[158:159], v[158:159], v[234:235]
	ds_read_b128 v[196:199], v71 offset:8192
	ds_read_b128 v[200:203], v71 offset:40960
	v_lshlrev_b32_e32 v212, 16, v36
	v_and_b32_e32 v213, 0xffff0000, v36
	v_lshlrev_b32_e32 v214, 16, v37
	v_and_b32_e32 v215, 0xffff0000, v37
	v_lshlrev_b32_e32 v216, 16, v34
	v_and_b32_e32 v217, 0xffff0000, v34
	v_lshlrev_b32_e32 v218, 16, v35
	v_and_b32_e32 v219, 0xffff0000, v35
	v_pk_mul_f32 v[212:213], v[228:229], v[212:213]
	v_pk_mul_f32 v[214:215], v[228:229], v[214:215]
	v_pk_mul_f32 v[216:217], v[230:231], v[216:217]
	v_pk_mul_f32 v[218:219], v[230:231], v[218:219]
	s_waitcnt lgkmcnt(2)
	v_pk_mul_f32 v[160:161], v[212:213], v[208:209]
	v_pk_mul_f32 v[162:163], v[214:215], v[210:211]
	v_pk_fma_f32 v[160:161], v[204:205], v[216:217], v[160:161]
	v_pk_fma_f32 v[162:163], v[206:207], v[218:219], v[162:163]
	v_pk_fma_f32 v[234:235], v[160:161], v[160:161], v[234:235]
	v_pk_fma_f32 v[234:235], v[162:163], v[162:163], v[234:235]
	ds_read_b128 v[204:207], v71 offset:9216
	ds_read_b128 v[208:211], v71 offset:41984
	v_lshlrev_b32_e32 v212, 16, v30
	v_and_b32_e32 v213, 0xffff0000, v30
	v_lshlrev_b32_e32 v214, 16, v31
	v_and_b32_e32 v215, 0xffff0000, v31
	v_lshlrev_b32_e32 v216, 16, v32
	v_and_b32_e32 v217, 0xffff0000, v32
	v_lshlrev_b32_e32 v218, 16, v33
	v_and_b32_e32 v219, 0xffff0000, v33
	v_pk_mul_f32 v[212:213], v[228:229], v[212:213]
	v_pk_mul_f32 v[214:215], v[228:229], v[214:215]
	v_pk_mul_f32 v[216:217], v[230:231], v[216:217]
	v_pk_mul_f32 v[218:219], v[230:231], v[218:219]
	s_waitcnt lgkmcnt(2)
; #define LAS __attribute__((address_space(3)))
; __device__ __forceinline__ float bflo(unsigned w) { return __uint_as_float(w << 16); }
; __device__ __forceinline__ float bfhi(unsigned w) { return __uint_as_float(w & 0xffff0000u); }
; template <int MODE> ...
;     ...
; #pragma unroll
;             for (int j = 0; j < 16; ++j) { const f32x4 g = *(const LAS f32x4*)(GP + lo4 + 256 * j), gi = *(const LAS f32x4*)(GI + lo4 + 256 * j);
;                 f32x4 x;
;                 x.x = bflo(pw[j].x) * ri * gi.x + bflo(hw[j].x) * rstd * g.x; x.y = bfhi(pw[j].x) * ri * gi.y + bfhi(hw[j].x) * rstd * g.y;
;                 x.z = bflo(pw[j].y) * ri * gi.z + bflo(hw[j].y) * rstd * g.z; x.w = bfhi(pw[j].y) * ri * gi.w + bfhi(hw[j].y) * rstd * g.w;
;                 if (MODE == 2) *(f32x4*)(xout + (size_t)row * DM + lo4 + 256 * j) = x;
;                 else ss2 += x.x * x.x + x.y * x.y + x.z * x.z + x.w * x.w;
;                 if (j & 1) __builtin_amdgcn_sched_barrier(0); }
	v_pk_mul_f32 v[164:165], v[212:213], v[200:201]
	v_pk_mul_f32 v[166:167], v[214:215], v[202:203]
	v_pk_fma_f32 v[164:165], v[196:197], v[216:217], v[164:165]
	v_pk_fma_f32 v[166:167], v[198:199], v[218:219], v[166:167]
	v_pk_fma_f32 v[234:235], v[164:165], v[164:165], v[234:235]
	v_pk_fma_f32 v[234:235], v[166:167], v[166:167], v[234:235]
	ds_read_b128 v[196:199], v71 offset:10240
	ds_read_b128 v[200:203], v71 offset:43008
	v_lshlrev_b32_e32 v212, 16, v26
	v_and_b32_e32 v213, 0xffff0000, v26
	v_lshlrev_b32_e32 v214, 16, v27
	v_and_b32_e32 v215, 0xffff0000, v27
	v_lshlrev_b32_e32 v216, 16, v28
	v_and_b32_e32 v217, 0xffff0000, v28
	v_lshlrev_b32_e32 v218, 16, v29
	v_and_b32_e32 v219, 0xffff0000, v29
	v_pk_mul_f32 v[212:213], v[228:229], v[212:213]
	v_pk_mul_f32 v[214:215], v[228:229], v[214:215]
	v_pk_mul_f32 v[216:217], v[230:231], v[216:217]
	v_pk_mul_f32 v[218:219], v[230:231], v[218:219]
	s_waitcnt lgkmcnt(2)
	v_pk_mul_f32 v[168:169], v[212:213], v[208:209]
	v_pk_mul_f32 v[170:171], v[214:215], v[210:211]
	v_pk_fma_f32 v[168:169], v[204:205], v[216:217], v[168:169]
	v_pk_fma_f32 v[170:171], v[206:207], v[218:219], v[170:171]
	v_pk_fma_f32 v[234:235], v[168:169], v[168:169], v[234:235]
	v_pk_fma_f32 v[234:235], v[170:171], v[170:171], v[234:235]
	ds_read_b128 v[204:207], v71 offset:11264
	ds_read_b128 v[208:211], v71 offset:44032
	v_lshlrev_b32_e32 v212, 16, v22
	v_and_b32_e32 v213, 0xffff0000, v22
	v_lshlrev_b32_e32 v214, 16, v23
	v_and_b32_e32 v215, 0xffff0000, v23
	v_lshlrev_b32_e32 v216, 16, v24
	v_and_b32_e32 v217, 0xffff0000, v24
	v_lshlrev_b32_e32 v218, 16, v25
	v_and_b32_e32 v219, 0xffff0000, v25
	v_pk_mul_f32 v[212:213], v[228:229], v[212:213]
	v_pk_mul_f32 v[214:215], v[228:229], v[214:215]
	v_pk_mul_f32 v[216:217], v[230:231], v[216:217]
	v_pk_mul_f32 v[218:219], v[230:231], v[218:219]
	s_waitcnt lgkmcnt(2)
	v_pk_mul_f32 v[172:173], v[212:213], v[200:201]
	v_pk_mul_f32 v[174:175], v[214:215], v[202:203]
	v_pk_fma_f32 v[172:173], v[196:197], v[216:217], v[172:173]
	v_pk_fma_f32 v[174:175], v[198:199], v[218:219], v[174:175]
	v_pk_fma_f32 v[234:235], v[172:173], v[172:173], v[234:235]
	v_pk_fma_f32 v[234:235], v[174:175], v[174:175], v[234:235]
	ds_read_b128 v[196:199], v71 offset:12288
	ds_read_b128 v[200:203], v71 offset:45056
	v_lshlrev_b32_e32 v212, 16, v18
	v_and_b32_e32 v213, 0xffff0000, v18
	v_lshlrev_b32_e32 v214, 16, v19
	v_and_b32_e32 v215, 0xffff0000, v19
	v_lshlrev_b32_e32 v216, 16, v20
	v_and_b32_e32 v217, 0xffff0000, v20
	v_lshlrev_b32_e32 v218, 16, v21
	v_and_b32_e32 v219, 0xffff0000, v21
	v_pk_mul_f32 v[212:213], v[228:229], v[212:213]
	v_pk_mul_f32 v[214:215], v[228:229], v[214:215]
	v_pk_mul_f32 v[216:217], v[230:231], v[216:217]
	v_pk_mul_f32 v[218:219], v[230:231], v[218:219]
	s_waitcnt lgkmcnt(2)
	v_pk_mul_f32 v[176:177], v[212:213], v[208:209]
	v_pk_mul_f32 v[178:179], v[214:215], v[210:211]
	v_pk_fma_f32 v[176:177], v[204:205], v[216:217], v[176:177]
	v_pk_fma_f32 v[178:179], v[206:207], v[218:219], v[178:179]
	v_pk_fma_f32 v[234:235], v[176:177], v[176:177], v[234:235]
	v_pk_fma_f32 v[234:235], v[178:179], v[178:179], v[234:235]
	ds_read_b128 v[204:207], v71 offset:13312
	ds_read_b128 v[208:211], v71 offset:46080
	v_lshlrev_b32_e32 v212, 16, v14
	v_and_b32_e32 v213, 0xffff0000, v14
	v_lshlrev_b32_e32 v214, 16, v15
	v_and_b32_e32 v215, 0xffff0000, v15
	v_lshlrev_b32_e32 v216, 16, v16
	v_and_b32_e32 v217, 0xffff0000, v16
	v_lshlrev_b32_e32 v218, 16, v17
	v_and_b32_e32 v219, 0xffff0000, v17
	v_pk_mul_f32 v[212:213], v[228:229], v[212:213]
	v_pk_mul_f32 v[214:215], v[228:229], v[214:215]
	v_pk_mul_f32 v[216:217], v[230:231], v[216:217]
	v_pk_mul_f32 v[218:219], v[230:231], v[218:219]
	s_waitcnt lgkmcnt(2)
; #define LAS __attribute__((address_space(3)))
; __device__ __forceinline__ float bflo(unsigned w) { return __uint_as_float(w << 16); }
; __device__ __forceinline__ float bfhi(unsigned w) { return __uint_as_float(w & 0xffff0000u); }
; template <int MODE> ...
;     ...
; #pragma unroll
;             for (int j = 0; j < 16; ++j) { const f32x4 g = *(const LAS f32x4*)(GP + lo4 + 256 * j), gi = *(const LAS f32x4*)(GI + lo4 + 256 * j);
;                 f32x4 x;
;                 x.x = bflo(pw[j].x) * ri * gi.x + bflo(hw[j].x) * rstd * g.x; x.y = bfhi(pw[j].x) * ri * gi.y + bfhi(hw[j].x) * rstd * g.y;
;                 x.z = bflo(pw[j].y) * ri * gi.z + bflo(hw[j].y) * rstd * g.z; x.w = bfhi(pw[j].y) * ri * gi.w + bfhi(hw[j].y) * rstd * g.w;
;                 if (MODE == 2) *(f32x4*)(xout + (size_t)row * DM + lo4 + 256 * j) = x;
;                 else ss2 += x.x * x.x + x.y * x.y + x.z * x.z + x.w * x.w;
;                 if (j & 1) __builtin_amdgcn_sched_barrier(0); }
;             if (MODE == 1) {
;                 const float rstd2 = rsqrtf(wave_sum(ss2) * (1.f / DM) + EPS);
;                 if (lane == 0) rs_out[row] = rstd2;
	v_pk_mul_f32 v[180:181], v[212:213], v[200:201]
	v_pk_mul_f32 v[182:183], v[214:215], v[202:203]
	v_pk_fma_f32 v[180:181], v[196:197], v[216:217], v[180:181]
	v_pk_fma_f32 v[182:183], v[198:199], v[218:219], v[182:183]
	v_pk_fma_f32 v[234:235], v[180:181], v[180:181], v[234:235]
	v_pk_fma_f32 v[234:235], v[182:183], v[182:183], v[234:235]
	ds_read_b128 v[196:199], v71 offset:14336
	ds_read_b128 v[200:203], v71 offset:47104
	v_lshlrev_b32_e32 v212, 16, v10
	v_and_b32_e32 v213, 0xffff0000, v10
	v_lshlrev_b32_e32 v214, 16, v11
	v_and_b32_e32 v215, 0xffff0000, v11
	v_lshlrev_b32_e32 v216, 16, v12
	v_and_b32_e32 v217, 0xffff0000, v12
	v_lshlrev_b32_e32 v218, 16, v13
	v_and_b32_e32 v219, 0xffff0000, v13
	v_pk_mul_f32 v[212:213], v[228:229], v[212:213]
	v_pk_mul_f32 v[214:215], v[228:229], v[214:215]
	v_pk_mul_f32 v[216:217], v[230:231], v[216:217]
	v_pk_mul_f32 v[218:219], v[230:231], v[218:219]
	s_waitcnt lgkmcnt(2)
	v_pk_mul_f32 v[184:185], v[212:213], v[208:209]
	v_pk_mul_f32 v[186:187], v[214:215], v[210:211]
	v_pk_fma_f32 v[184:185], v[204:205], v[216:217], v[184:185]
	v_pk_fma_f32 v[186:187], v[206:207], v[218:219], v[186:187]
	v_pk_fma_f32 v[234:235], v[184:185], v[184:185], v[234:235]
	v_pk_fma_f32 v[234:235], v[186:187], v[186:187], v[234:235]
	ds_read_b128 v[204:207], v71 offset:15360
	ds_read_b128 v[208:211], v71 offset:48128
	v_lshlrev_b32_e32 v212, 16, v6
	v_and_b32_e32 v213, 0xffff0000, v6
	v_lshlrev_b32_e32 v214, 16, v7
	v_and_b32_e32 v215, 0xffff0000, v7
	v_lshlrev_b32_e32 v216, 16, v8
	v_and_b32_e32 v217, 0xffff0000, v8
	v_lshlrev_b32_e32 v218, 16, v9
	v_and_b32_e32 v219, 0xffff0000, v9
	v_pk_mul_f32 v[212:213], v[228:229], v[212:213]
	v_pk_mul_f32 v[214:215], v[228:229], v[214:215]
	v_pk_mul_f32 v[216:217], v[230:231], v[216:217]
	v_pk_mul_f32 v[218:219], v[230:231], v[218:219]
	s_waitcnt lgkmcnt(2)
	v_pk_mul_f32 v[188:189], v[212:213], v[200:201]
	v_pk_mul_f32 v[190:191], v[214:215], v[202:203]
	v_pk_fma_f32 v[188:189], v[196:197], v[216:217], v[188:189]
	v_pk_fma_f32 v[190:191], v[198:199], v[218:219], v[190:191]
	v_pk_fma_f32 v[234:235], v[188:189], v[188:189], v[234:235]
	v_pk_fma_f32 v[234:235], v[190:191], v[190:191], v[234:235]
	v_lshlrev_b32_e32 v212, 16, v2
	v_and_b32_e32 v213, 0xffff0000, v2
	v_lshlrev_b32_e32 v214, 16, v3
	v_and_b32_e32 v215, 0xffff0000, v3
	v_lshlrev_b32_e32 v216, 16, v4
	v_and_b32_e32 v217, 0xffff0000, v4
	v_lshlrev_b32_e32 v218, 16, v5
	v_and_b32_e32 v219, 0xffff0000, v5
	v_pk_mul_f32 v[212:213], v[228:229], v[212:213]
	v_pk_mul_f32 v[214:215], v[228:229], v[214:215]
	v_pk_mul_f32 v[216:217], v[230:231], v[216:217]
	v_pk_mul_f32 v[218:219], v[230:231], v[218:219]
	s_waitcnt lgkmcnt(0)
	v_pk_mul_f32 v[192:193], v[212:213], v[208:209]
	v_pk_mul_f32 v[194:195], v[214:215], v[210:211]
	v_pk_fma_f32 v[192:193], v[204:205], v[216:217], v[192:193]
	v_pk_fma_f32 v[194:195], v[206:207], v[218:219], v[194:195]
	v_pk_fma_f32 v[234:235], v[192:193], v[192:193], v[234:235]
	v_pk_fma_f32 v[234:235], v[194:195], v[194:195], v[234:235]
	v_add_f32_e32 v77, v234, v235
	ds_bpermute_b32 v70, v70, v77
	s_waitcnt lgkmcnt(0)
	v_add_f32_e32 v70, v77, v70
	ds_bpermute_b32 v72, v72, v70
	s_waitcnt lgkmcnt(0)
	v_add_f32_e32 v70, v70, v72
	ds_bpermute_b32 v72, v73, v70
	s_waitcnt lgkmcnt(0)
	v_add_f32_e32 v70, v70, v72
	ds_bpermute_b32 v72, v74, v70
	s_waitcnt lgkmcnt(0)
	v_add_f32_e32 v70, v70, v72
	ds_bpermute_b32 v72, v75, v70
	s_waitcnt lgkmcnt(0)
	v_add_f32_e32 v70, v70, v72
	ds_bpermute_b32 v72, v76, v70
	s_waitcnt lgkmcnt(0)
	v_add_f32_e32 v70, v70, v72
	v_fmamk_f32 v70, v70, 0x39800000, v99
	v_mul_f32_e32 v72, 0x4b800000, v70
	v_cmp_gt_f32_e32 vcc, s66, v70
	s_nop 1
	v_cndmask_b32_e32 v70, v70, v72, vcc
	v_rsq_f32_e32 v70, v70
	s_nop 0
	v_mul_f32_e32 v72, 0x45800000, v70
	v_cndmask_b32_e32 v70, v70, v72, vcc
	s_and_saveexec_b64 s[6:7], s[4:5]
	s_cbranch_execz .LBB0_775
	global_store_dword v98, v70, s[62:63]
	s_branch .LBB0_775

; #define LAS __attribute__((address_space(3)))
; template <int MODE> ...
;     ...
;     LAS float* GP = (LAS float*)lds; LAS float* GN = (LAS float*)(lds + 16384); LAS float* GI = (LAS float*)(lds + 32768);
;     __syncthreads();
; #pragma unroll
;     for (int i = 0; i < 2; ++i) { const int o = 4 * (tid + NTHREADS * i);
;         if (MODE != 0) { *(LAS f32x4*)(GP + o) = *(const f32x4*)(gpost + o); const f32x4 g = *(const f32x4*)(gprev + o); *(LAS f32x4*)(GI + o) = (f32x4){1.f / g.x, 1.f / g.y, 1.f / g.z, 1.f / g.w}; }
;         if (MODE != 2) *(LAS f32x4*)(GN + o) = *(const f32x4*)(gpre + o); }
;     __syncthreads();
;     const int lo4 = 4 * lane;
; #pragma unroll 1
;     for (int row = gw; row < SEQ; row += NGW) {
.LBB0_1115:
	s_cmp_gt_i32 s36, 10
	s_cselect_b64 s[6:7], -1, 0
	s_xor_b64 s[4:5], s[4:5], -1
	s_or_b64 s[4:5], s[6:7], s[4:5]
	s_and_b64 vcc, exec, s[4:5]
	s_cbranch_vccnz .LBB0_1121
	s_mov_b64 s[12:13], 0
	s_waitcnt vmcnt(0)
	v_mbcnt_lo_u32_b32 v2, -1, 0
	v_mbcnt_hi_u32_b32 v2, -1, v2
	s_load_dwordx4 s[4:7], s[0:1], 0x70
	s_load_dwordx2 s[8:9], s[0:1], 0xa8
	v_lshlrev_b32_e32 v0, 2, v2
	v_lshl_add_u32 v24, s89, 8, v0
	v_ashrrev_i32_e32 v25, 31, v24
	v_lshlrev_b64 v[12:13], 2, v[24:25]
	v_add_u32_e32 v16, 0x800, v24
	s_waitcnt lgkmcnt(0)
	v_lshl_add_u64 v[8:9], s[4:5], 0, v[12:13]
	v_ashrrev_i32_e32 v17, 31, v16
	s_barrier
	v_lshl_add_u64 v[4:5], s[6:7], 0, v[12:13]
	global_load_dwordx4 v[8:11], v[8:9], off
	v_lshl_add_u64 v[12:13], s[8:9], 0, v[12:13]
	v_lshlrev_b64 v[26:27], 2, v[16:17]
	global_load_dwordx4 v[4:7], v[4:5], off
	v_lshl_add_u64 v[16:17], s[6:7], 0, v[26:27]
	global_load_dwordx4 v[12:15], v[12:13], off
	v_lshl_add_u64 v[20:21], s[4:5], 0, v[26:27]
	global_load_dwordx4 v[16:19], v[16:17], off
	v_lshl_add_u32 v1, v24, 2, 0
	global_load_dwordx4 v[20:23], v[20:21], off
	v_lshl_add_u64 v[24:25], s[8:9], 0, v[26:27]
	global_load_dwordx4 v[24:27], v[24:25], off
	s_cmpk_gt_i32 s40, 0x1fff
	s_waitcnt vmcnt(5)
	v_div_scale_f32 v3, s[4:5], v8, v8, 1.0
	v_div_scale_f32 v29, s[8:9], v11, v11, 1.0
	s_waitcnt vmcnt(4)
	ds_write_b128 v1, v[4:7]
	v_div_scale_f32 v5, s[4:5], v9, v9, 1.0
	s_waitcnt vmcnt(3)
	ds_write_b128 v1, v[12:15] offset:16384
	v_rcp_f32_e32 v12, v3
	v_div_scale_f32 v7, s[6:7], v10, v10, 1.0
	v_rcp_f32_e32 v13, v5
	s_waitcnt vmcnt(2)
	ds_write_b128 v1, v[16:19] offset:8192
	s_waitcnt vmcnt(1)
	v_div_scale_f32 v16, s[10:11], v20, v20, 1.0
	v_rcp_f32_e32 v14, v7
	v_rcp_f32_e32 v19, v16
	v_rcp_f32_e32 v15, v29
	v_fma_f32 v32, -v3, v12, 1.0
	v_div_scale_f32 v4, vcc, 1.0, v8, 1.0
	v_fma_f32 v33, -v5, v13, 1.0
	v_fmac_f32_e32 v12, v32, v12
	v_div_scale_f32 v6, s[4:5], 1.0, v9, 1.0
	v_fma_f32 v34, -v7, v14, 1.0
	v_fmac_f32_e32 v13, v33, v13
	v_fma_f32 v32, -v16, v19, 1.0
	v_mul_f32_e32 v33, v4, v12
	v_div_scale_f32 v28, s[6:7], 1.0, v10, 1.0
	v_fma_f32 v35, -v29, v15, 1.0
	v_fmac_f32_e32 v14, v34, v14
	v_mul_f32_e32 v34, v6, v13
	v_fmac_f32_e32 v19, v32, v19
	v_fma_f32 v32, -v3, v33, v4
	v_div_scale_f32 v30, s[8:9], 1.0, v11, 1.0
	v_fmac_f32_e32 v15, v35, v15
	v_mul_f32_e32 v35, v28, v14
	v_fma_f32 v37, -v5, v34, v6
	v_fmac_f32_e32 v33, v32, v12
	v_div_scale_f32 v17, s[10:11], 1.0, v20, 1.0
	v_mul_f32_e32 v36, v30, v15
	v_fma_f32 v38, -v7, v35, v28
	v_fmac_f32_e32 v34, v37, v13
	v_fma_f32 v3, -v3, v33, v4
	v_div_scale_f32 v18, s[14:15], v21, v21, 1.0
	v_fma_f32 v39, -v29, v36, v30
	v_mul_f32_e32 v40, v17, v19
	v_fmac_f32_e32 v35, v38, v14
	v_fma_f32 v5, -v5, v34, v6
	v_div_fmas_f32 v3, v3, v12, v33
	s_mov_b64 vcc, s[4:5]
	v_rcp_f32_e32 v31, v18
	v_fmac_f32_e32 v36, v39, v15
	v_fma_f32 v32, -v16, v40, v17
	v_fma_f32 v6, -v7, v35, v28
	v_div_fixup_f32 v4, v3, v8, 1.0
	v_div_fmas_f32 v3, v5, v13, v34
	s_mov_b64 vcc, s[6:7]
	v_fma_f32 v7, -v29, v36, v30
	v_fmac_f32_e32 v40, v32, v19
	v_div_fixup_f32 v5, v3, v9, 1.0
	v_div_fmas_f32 v3, v6, v14, v35
	s_mov_b64 vcc, s[8:9]
	v_fma_f32 v12, -v16, v40, v17
	v_div_fixup_f32 v6, v3, v10, 1.0
	v_div_fmas_f32 v3, v7, v15, v36
	s_mov_b64 vcc, s[10:11]
	v_div_fixup_f32 v7, v3, v11, 1.0
	v_div_fmas_f32 v3, v12, v19, v40
	ds_write_b128 v1, v[4:7] offset:32768
	v_div_fixup_f32 v4, v3, v20, 1.0
	v_fma_f32 v3, -v18, v31, 1.0
	v_fmac_f32_e32 v31, v3, v31
	v_div_scale_f32 v3, vcc, 1.0, v21, 1.0
	v_mul_f32_e32 v5, v3, v31
	v_fma_f32 v6, -v18, v5, v3
	v_fmac_f32_e32 v5, v6, v31
	v_div_scale_f32 v6, s[4:5], v22, v22, 1.0
	v_rcp_f32_e32 v7, v6
	v_fma_f32 v3, -v18, v5, v3
	v_div_fmas_f32 v3, v3, v31, v5
	v_div_fixup_f32 v5, v3, v21, 1.0
	v_fma_f32 v3, -v6, v7, 1.0
	v_fmac_f32_e32 v7, v3, v7
	v_div_scale_f32 v3, vcc, 1.0, v22, 1.0
	v_mul_f32_e32 v8, v3, v7
	v_fma_f32 v9, -v6, v8, v3
	v_fmac_f32_e32 v8, v9, v7
	v_div_scale_f32 v9, s[4:5], v23, v23, 1.0
	v_rcp_f32_e32 v10, v9
	v_fma_f32 v3, -v6, v8, v3
	v_div_fmas_f32 v3, v3, v7, v8
	v_div_fixup_f32 v6, v3, v22, 1.0
	v_fma_f32 v3, -v9, v10, 1.0
	v_fmac_f32_e32 v10, v3, v10
	v_div_scale_f32 v3, vcc, 1.0, v23, 1.0
	v_mul_f32_e32 v7, v3, v10
	v_fma_f32 v8, -v9, v7, v3
	v_fmac_f32_e32 v7, v8, v10
	v_fma_f32 v3, -v9, v7, v3
	v_div_fmas_f32 v3, v3, v10, v7
	v_div_fixup_f32 v7, v3, v23, 1.0
	ds_write_b128 v1, v[4:7] offset:40960
	s_waitcnt vmcnt(0)
	ds_write_b128 v1, v[24:27] offset:24576
	s_waitcnt lgkmcnt(0)
	s_barrier
	s_cbranch_scc1 .LBB0_1121
	s_load_dwordx2 s[6:7], s[0:1], 0xe8
	s_ashr_i32 s41, s40, 31
	s_lshl_b64 s[8:9], s[40:41], 2
	v_ashrrev_i32_e32 v1, 31, v0
	v_cmp_eq_u32_e64 s[4:5], 0, v2
	s_waitcnt lgkmcnt(0)
	s_add_u32 s8, s6, s8
	s_addc_u32 s9, s7, s9
	s_add_u32 s64, s8, 0x2c0000
	s_addc_u32 s65, s9, 0
	s_ashr_i32 s39, s38, 31
	s_lshl_b64 s[8:9], s[38:39], 2
	s_lshl_b64 s[10:11], s[40:41], 13
	s_add_u32 s6, s6, s10
	s_addc_u32 s7, s7, s11
	v_mbcnt_lo_u32_b32 v2, -1, 0
	v_lshl_add_u32 v71, v0, 2, 0
	v_lshl_add_u64 v[0:1], v[0:1], 1, s[6:7]
	s_lshl_b64 s[10:11], s[38:39], 13
	s_mov_b64 s[14:15], 0x3000000
	s_mov_b64 s[18:19], 0x3000200
	s_mov_b64 s[20:21], 0x3000400
	s_mov_b64 s[22:23], 0x3000600
	s_mov_b64 s[24:25], 0x3000800
	s_mov_b64 s[26:27], 0x3000a00
	s_mov_b64 s[42:43], 0x3000c00
	s_mov_b64 s[44:45], 0x3000e00
	s_mov_b64 s[46:47], 0x3001000
	s_mov_b32 s39, 0x3001000
	s_mov_b32 s41, 0x7001000
	s_mov_b64 s[48:49], 0x3001200
	s_mov_b64 s[50:51], 0x3001400
	s_mov_b64 s[52:53], 0x3001600
	s_mov_b64 s[54:55], 0x3001800
	s_mov_b64 s[56:57], 0x3001a00
	s_mov_b64 s[58:59], 0x3001c00
	s_mov_b64 s[60:61], 0x3001e00
	v_mov_b32_e32 v79, 0
	v_mov_b32_e32 v100, 0x358637bd
	s_mov_b32 s66, 0x800000
	v_mbcnt_hi_u32_b32 v101, -1, v2
	s_mov_b32 s67, s40
	s_mov_b32 s96, 0x3000000
	s_mov_b32 s97, 0x3001000
	v_mbcnt_lo_u32_b32 v236, -1, 0
	v_mbcnt_hi_u32_b32 v236, -1, v236
	v_and_b32_e32 v236, 1, v236
	v_mul_u32_u24_e32 v236, 0x1f8, v236
	s_branch .LBB0_1119

; template <int MODE> ...
;     ...
;             const bf16* pr = xn + (size_t)row * DM; bf16* pw_out = xn_out + (size_t)row * DM; const bf16* hr = hb + (size_t)row * DM;
;             v2u pw[16], hw[16]; float ss = 0.f;
; #pragma unroll
;             for (int j = 0; j < 16; ++j) { pw[j] = *(const v2u*)(pr + lo4 + 256 * j); hw[j] = *(const v2u*)(hr + lo4 + 256 * j); }
.LBB0_1119:
	v_lshl_add_u64 v[68:69], v[0:1], 0, s[12:13]
	s_add_u32 s62, s64, s12
	s_addc_u32 s63, s65, s13
	global_load_dword v78, v79, s[62:63]
	v_add_co_u32_e32 v196, vcc, v236, v68
	s_nop 1
	v_addc_co_u32_e32 v197, vcc, 0, v69, vcc
	v_add_co_u32_e32 v198, vcc, 0x7000000, v196
	s_nop 1
	v_addc_co_u32_e32 v199, vcc, 0, v197, vcc
	v_add_co_u32_e32 v200, vcc, 0x7001000, v196
	s_nop 1
	v_addc_co_u32_e32 v201, vcc, 0, v197, vcc
	v_add_co_u32_e32 v202, vcc, 0x3000000, v196
	s_nop 1
	v_addc_co_u32_e32 v203, vcc, 0, v197, vcc
	v_add_co_u32_e32 v204, vcc, 0x3001000, v196
	s_nop 1
	v_addc_co_u32_e32 v205, vcc, 0, v197, vcc
	global_load_dwordx4 v[132:135], v[198:199], off
	global_load_dwordx4 v[136:139], v[198:199], off offset:1024
	global_load_dwordx4 v[140:143], v[198:199], off offset:2048
	global_load_dwordx4 v[144:147], v[198:199], off offset:3072
	global_load_dwordx4 v[148:151], v[200:201], off
	global_load_dwordx4 v[152:155], v[200:201], off offset:1024
	global_load_dwordx4 v[156:159], v[200:201], off offset:2048
	global_load_dwordx4 v[160:163], v[200:201], off offset:3072
	global_load_dwordx4 v[164:167], v[202:203], off
	global_load_dwordx4 v[168:171], v[202:203], off offset:1024
	global_load_dwordx4 v[172:175], v[202:203], off offset:2048
	global_load_dwordx4 v[176:179], v[202:203], off offset:3072
	global_load_dwordx4 v[180:183], v[204:205], off
	global_load_dwordx4 v[184:187], v[204:205], off offset:1024
	global_load_dwordx4 v[188:191], v[204:205], off offset:2048
	global_load_dwordx4 v[192:195], v[204:205], off offset:3072
	s_waitcnt vmcnt(0)
	s_mov_b32 vcc_lo, 0x55555555
	s_mov_b32 vcc_hi, 0x55555555
	s_nop 1
	v_cndmask_b32_dpp v60, v134, v132, vcc quad_perm:[1,0,3,2] row_mask:0xf bank_mask:0xf
	v_cndmask_b32_dpp v61, v135, v133, vcc quad_perm:[1,0,3,2] row_mask:0xf bank_mask:0xf
	v_cndmask_b32_dpp v54, v138, v136, vcc quad_perm:[1,0,3,2] row_mask:0xf bank_mask:0xf
	v_cndmask_b32_dpp v55, v139, v137, vcc quad_perm:[1,0,3,2] row_mask:0xf bank_mask:0xf
	v_cndmask_b32_dpp v46, v142, v140, vcc quad_perm:[1,0,3,2] row_mask:0xf bank_mask:0xf
	v_cndmask_b32_dpp v47, v143, v141, vcc quad_perm:[1,0,3,2] row_mask:0xf bank_mask:0xf
	v_cndmask_b32_dpp v40, v146, v144, vcc quad_perm:[1,0,3,2] row_mask:0xf bank_mask:0xf
	v_cndmask_b32_dpp v41, v147, v145, vcc quad_perm:[1,0,3,2] row_mask:0xf bank_mask:0xf
	v_cndmask_b32_dpp v34, v150, v148, vcc quad_perm:[1,0,3,2] row_mask:0xf bank_mask:0xf
	v_cndmask_b32_dpp v35, v151, v149, vcc quad_perm:[1,0,3,2] row_mask:0xf bank_mask:0xf
	v_cndmask_b32_dpp v24, v154, v152, vcc quad_perm:[1,0,3,2] row_mask:0xf bank_mask:0xf
	v_cndmask_b32_dpp v25, v155, v153, vcc quad_perm:[1,0,3,2] row_mask:0xf bank_mask:0xf
	v_cndmask_b32_dpp v16, v158, v156, vcc quad_perm:[1,0,3,2] row_mask:0xf bank_mask:0xf
	v_cndmask_b32_dpp v17, v159, v157, vcc quad_perm:[1,0,3,2] row_mask:0xf bank_mask:0xf
	v_cndmask_b32_dpp v8, v162, v160, vcc quad_perm:[1,0,3,2] row_mask:0xf bank_mask:0xf
	v_cndmask_b32_dpp v9, v163, v161, vcc quad_perm:[1,0,3,2] row_mask:0xf bank_mask:0xf
	v_cndmask_b32_dpp v66, v166, v164, vcc quad_perm:[1,0,3,2] row_mask:0xf bank_mask:0xf
	v_cndmask_b32_dpp v67, v167, v165, vcc quad_perm:[1,0,3,2] row_mask:0xf bank_mask:0xf
	v_cndmask_b32_dpp v62, v170, v168, vcc quad_perm:[1,0,3,2] row_mask:0xf bank_mask:0xf
	v_cndmask_b32_dpp v63, v171, v169, vcc quad_perm:[1,0,3,2] row_mask:0xf bank_mask:0xf
	v_cndmask_b32_dpp v52, v174, v172, vcc quad_perm:[1,0,3,2] row_mask:0xf bank_mask:0xf
	v_cndmask_b32_dpp v53, v175, v173, vcc quad_perm:[1,0,3,2] row_mask:0xf bank_mask:0xf
	v_cndmask_b32_dpp v42, v178, v176, vcc quad_perm:[1,0,3,2] row_mask:0xf bank_mask:0xf
	v_cndmask_b32_dpp v43, v179, v177, vcc quad_perm:[1,0,3,2] row_mask:0xf bank_mask:0xf
	v_cndmask_b32_dpp v32, v182, v180, vcc quad_perm:[1,0,3,2] row_mask:0xf bank_mask:0xf
	v_cndmask_b32_dpp v33, v183, v181, vcc quad_perm:[1,0,3,2] row_mask:0xf bank_mask:0xf
	v_cndmask_b32_dpp v22, v186, v184, vcc quad_perm:[1,0,3,2] row_mask:0xf bank_mask:0xf
	v_cndmask_b32_dpp v23, v187, v185, vcc quad_perm:[1,0,3,2] row_mask:0xf bank_mask:0xf
	v_cndmask_b32_dpp v14, v190, v188, vcc quad_perm:[1,0,3,2] row_mask:0xf bank_mask:0xf
	v_cndmask_b32_dpp v15, v191, v189, vcc quad_perm:[1,0,3,2] row_mask:0xf bank_mask:0xf
	v_cndmask_b32_dpp v6, v194, v192, vcc quad_perm:[1,0,3,2] row_mask:0xf bank_mask:0xf
	v_cndmask_b32_dpp v7, v195, v193, vcc quad_perm:[1,0,3,2] row_mask:0xf bank_mask:0xf
	s_mov_b32 vcc_lo, 0xaaaaaaaa
	s_mov_b32 vcc_hi, 0xaaaaaaaa
	s_nop 1
	v_cndmask_b32_dpp v56, v132, v134, vcc quad_perm:[1,0,3,2] row_mask:0xf bank_mask:0xf
	v_cndmask_b32_dpp v57, v133, v135, vcc quad_perm:[1,0,3,2] row_mask:0xf bank_mask:0xf
	v_cndmask_b32_dpp v50, v136, v138, vcc quad_perm:[1,0,3,2] row_mask:0xf bank_mask:0xf
	v_cndmask_b32_dpp v51, v137, v139, vcc quad_perm:[1,0,3,2] row_mask:0xf bank_mask:0xf
	v_cndmask_b32_dpp v44, v140, v142, vcc quad_perm:[1,0,3,2] row_mask:0xf bank_mask:0xf
	v_cndmask_b32_dpp v45, v141, v143, vcc quad_perm:[1,0,3,2] row_mask:0xf bank_mask:0xf
	v_cndmask_b32_dpp v36, v144, v146, vcc quad_perm:[1,0,3,2] row_mask:0xf bank_mask:0xf
	v_cndmask_b32_dpp v37, v145, v147, vcc quad_perm:[1,0,3,2] row_mask:0xf bank_mask:0xf
	v_cndmask_b32_dpp v30, v148, v150, vcc quad_perm:[1,0,3,2] row_mask:0xf bank_mask:0xf
	v_cndmask_b32_dpp v31, v149, v151, vcc quad_perm:[1,0,3,2] row_mask:0xf bank_mask:0xf
	v_cndmask_b32_dpp v20, v152, v154, vcc quad_perm:[1,0,3,2] row_mask:0xf bank_mask:0xf
	v_cndmask_b32_dpp v21, v153, v155, vcc quad_perm:[1,0,3,2] row_mask:0xf bank_mask:0xf
	v_cndmask_b32_dpp v12, v156, v158, vcc quad_perm:[1,0,3,2] row_mask:0xf bank_mask:0xf
; __device__ __forceinline__ float bflo(unsigned w) { return __uint_as_float(w << 16); }
; __device__ __forceinline__ float bfhi(unsigned w) { return __uint_as_float(w & 0xffff0000u); }
; template <int MODE> ...
;     ...
;             const bf16* pr = xn + (size_t)row * DM; bf16* pw_out = xn_out + (size_t)row * DM; const bf16* hr = hb + (size_t)row * DM;
;             v2u pw[16], hw[16]; float ss = 0.f;
; #pragma unroll
;             for (int j = 0; j < 16; ++j) { pw[j] = *(const v2u*)(pr + lo4 + 256 * j); hw[j] = *(const v2u*)(hr + lo4 + 256 * j); }
;             const float ri = 1.f / rs[row];
; #pragma unroll
;             for (int j = 0; j < 16; ++j) { const float a = bflo(hw[j].x), b = bfhi(hw[j].x), c = bflo(hw[j].y), d = bfhi(hw[j].y); ss += a * a + b * b + c * c + d * d; }
	v_cndmask_b32_dpp v13, v157, v159, vcc quad_perm:[1,0,3,2] row_mask:0xf bank_mask:0xf
	v_cndmask_b32_dpp v4, v160, v162, vcc quad_perm:[1,0,3,2] row_mask:0xf bank_mask:0xf
	v_cndmask_b32_dpp v5, v161, v163, vcc quad_perm:[1,0,3,2] row_mask:0xf bank_mask:0xf
	v_cndmask_b32_dpp v64, v164, v166, vcc quad_perm:[1,0,3,2] row_mask:0xf bank_mask:0xf
	v_cndmask_b32_dpp v65, v165, v167, vcc quad_perm:[1,0,3,2] row_mask:0xf bank_mask:0xf
	v_cndmask_b32_dpp v58, v168, v170, vcc quad_perm:[1,0,3,2] row_mask:0xf bank_mask:0xf
	v_cndmask_b32_dpp v59, v169, v171, vcc quad_perm:[1,0,3,2] row_mask:0xf bank_mask:0xf
	v_cndmask_b32_dpp v48, v172, v174, vcc quad_perm:[1,0,3,2] row_mask:0xf bank_mask:0xf
	v_cndmask_b32_dpp v49, v173, v175, vcc quad_perm:[1,0,3,2] row_mask:0xf bank_mask:0xf
	v_cndmask_b32_dpp v38, v176, v178, vcc quad_perm:[1,0,3,2] row_mask:0xf bank_mask:0xf
	v_cndmask_b32_dpp v39, v177, v179, vcc quad_perm:[1,0,3,2] row_mask:0xf bank_mask:0xf
	v_cndmask_b32_dpp v28, v180, v182, vcc quad_perm:[1,0,3,2] row_mask:0xf bank_mask:0xf
	v_cndmask_b32_dpp v29, v181, v183, vcc quad_perm:[1,0,3,2] row_mask:0xf bank_mask:0xf
	v_cndmask_b32_dpp v18, v184, v186, vcc quad_perm:[1,0,3,2] row_mask:0xf bank_mask:0xf
	v_cndmask_b32_dpp v19, v185, v187, vcc quad_perm:[1,0,3,2] row_mask:0xf bank_mask:0xf
	v_cndmask_b32_dpp v10, v188, v190, vcc quad_perm:[1,0,3,2] row_mask:0xf bank_mask:0xf
	v_cndmask_b32_dpp v11, v189, v191, vcc quad_perm:[1,0,3,2] row_mask:0xf bank_mask:0xf
	v_cndmask_b32_dpp v2, v192, v194, vcc quad_perm:[1,0,3,2] row_mask:0xf bank_mask:0xf
	v_cndmask_b32_dpp v3, v193, v195, vcc quad_perm:[1,0,3,2] row_mask:0xf bank_mask:0xf
	v_lshlrev_b32_e32 v70, 16, v61
	v_and_b32_e32 v27, 0xffff0000, v60
	s_waitcnt vmcnt(31)
	v_and_b32_e32 v74, 0xffff0000, v56
	v_lshlrev_b32_e32 v26, 16, v60
	v_lshlrev_b32_e32 v73, 16, v56
	v_mul_f32_e32 v27, v27, v27
	v_mul_f32_e32 v74, v74, v74
	v_lshlrev_b32_e32 v75, 16, v57
	s_waitcnt vmcnt(30)
	v_and_b32_e32 v80, 0xffff0000, v54
	v_fmac_f32_e32 v27, v26, v26
	v_fmac_f32_e32 v74, v73, v73
	v_and_b32_e32 v72, 0xffff0000, v61
	v_and_b32_e32 v76, 0xffff0000, v57
	v_lshlrev_b32_e32 v77, 16, v54
	s_waitcnt vmcnt(29)
	v_and_b32_e32 v84, 0xffff0000, v50
	s_waitcnt vmcnt(28)
	v_and_b32_e32 v88, 0xffff0000, v46
	v_mul_f32_e32 v80, v80, v80
	v_fmac_f32_e32 v27, v70, v70
	v_fmac_f32_e32 v74, v75, v75
	v_lshlrev_b32_e32 v81, 16, v55
	v_lshlrev_b32_e32 v83, 16, v50
	v_lshlrev_b32_e32 v87, 16, v46
	v_mul_f32_e32 v84, v84, v84
	v_fmac_f32_e32 v80, v77, v77
	v_fmac_f32_e32 v27, v72, v72
	v_fmac_f32_e32 v74, v76, v76
	v_mul_f32_e32 v72, v88, v88
	v_and_b32_e32 v82, 0xffff0000, v55
	v_lshlrev_b32_e32 v85, 16, v51
	v_fmac_f32_e32 v84, v83, v83
	v_fmac_f32_e32 v80, v81, v81
	v_add_f32_e32 v26, v27, v74
	v_lshlrev_b32_e32 v27, 16, v47
	v_fmac_f32_e32 v72, v87, v87
	v_and_b32_e32 v86, 0xffff0000, v51
	v_fmac_f32_e32 v84, v85, v85
	v_fmac_f32_e32 v80, v82, v82
	v_and_b32_e32 v70, 0xffff0000, v47
	v_fmac_f32_e32 v72, v27, v27
	v_fmac_f32_e32 v84, v86, v86
	v_add_f32_e32 v26, v26, v80
	v_fmac_f32_e32 v72, v70, v70
	s_waitcnt vmcnt(27)
	v_and_b32_e32 v70, 0xffff0000, v44
	v_add_f32_e32 v26, v26, v84
	v_lshlrev_b32_e32 v27, 16, v44
	v_mul_f32_e32 v70, v70, v70
	v_add_f32_e32 v26, v26, v72
	v_lshlrev_b32_e32 v72, 16, v45
	v_fmac_f32_e32 v70, v27, v27
	v_and_b32_e32 v73, 0xffff0000, v45
	v_fmac_f32_e32 v70, v72, v72
	v_fmac_f32_e32 v70, v73, v73
	v_add_f32_e32 v26, v26, v70
	s_waitcnt vmcnt(26)
	v_and_b32_e32 v70, 0xffff0000, v40
	v_lshlrev_b32_e32 v27, 16, v40
	v_mul_f32_e32 v70, v70, v70
	v_lshlrev_b32_e32 v72, 16, v41
	v_fmac_f32_e32 v70, v27, v27
	v_and_b32_e32 v73, 0xffff0000, v41
	v_fmac_f32_e32 v70, v72, v72
	v_fmac_f32_e32 v70, v73, v73
	v_add_f32_e32 v26, v26, v70
	s_waitcnt vmcnt(17)
	v_and_b32_e32 v70, 0xffff0000, v36
	v_lshlrev_b32_e32 v27, 16, v36
	v_mul_f32_e32 v70, v70, v70
	v_lshlrev_b32_e32 v72, 16, v37
	v_fmac_f32_e32 v70, v27, v27
	v_and_b32_e32 v73, 0xffff0000, v37
	v_fmac_f32_e32 v70, v72, v72
	v_fmac_f32_e32 v70, v73, v73
	v_add_f32_e32 v26, v26, v70
	v_and_b32_e32 v70, 0xffff0000, v34
	v_lshlrev_b32_e32 v27, 16, v34
	v_mul_f32_e32 v70, v70, v70
	v_lshlrev_b32_e32 v72, 16, v35
	v_fmac_f32_e32 v70, v27, v27
	v_and_b32_e32 v73, 0xffff0000, v35
	v_fmac_f32_e32 v70, v72, v72
	v_fmac_f32_e32 v70, v73, v73
	v_add_f32_e32 v26, v26, v70
	v_and_b32_e32 v70, 0xffff0000, v30
	v_lshlrev_b32_e32 v27, 16, v30
	v_mul_f32_e32 v70, v70, v70
	v_lshlrev_b32_e32 v72, 16, v31
	v_fmac_f32_e32 v70, v27, v27
	v_and_b32_e32 v73, 0xffff0000, v31
	v_fmac_f32_e32 v70, v72, v72
	v_fmac_f32_e32 v70, v73, v73
	v_add_f32_e32 v26, v26, v70
	v_and_b32_e32 v70, 0xffff0000, v24
	v_lshlrev_b32_e32 v27, 16, v24
	v_mul_f32_e32 v70, v70, v70
	v_lshlrev_b32_e32 v72, 16, v25
	v_fmac_f32_e32 v70, v27, v27
	v_and_b32_e32 v73, 0xffff0000, v25
	v_fmac_f32_e32 v70, v72, v72
	v_fmac_f32_e32 v70, v73, v73
	v_add_f32_e32 v26, v26, v70
	v_and_b32_e32 v70, 0xffff0000, v20
	v_lshlrev_b32_e32 v27, 16, v20
	v_mul_f32_e32 v70, v70, v70
	v_lshlrev_b32_e32 v72, 16, v21
	v_fmac_f32_e32 v70, v27, v27
	v_and_b32_e32 v73, 0xffff0000, v21
	v_fmac_f32_e32 v70, v72, v72
	v_fmac_f32_e32 v70, v73, v73
	s_waitcnt vmcnt(11)
	v_and_b32_e32 v73, 0xffff0000, v12
	v_and_b32_e32 v72, 0xffff0000, v16
	v_add_f32_e32 v70, v26, v70
	v_lshlrev_b32_e32 v27, 16, v12
	v_lshlrev_b32_e32 v26, 16, v16
	v_pk_mul_f32 v[72:73], v[72:73], v[72:73]
	v_lshlrev_b32_e32 v75, 16, v13
	v_lshlrev_b32_e32 v74, 16, v17
	v_pk_fma_f32 v[26:27], v[26:27], v[26:27], v[72:73]
	v_and_b32_e32 v77, 0xffff0000, v13
	v_and_b32_e32 v76, 0xffff0000, v17
	v_pk_fma_f32 v[26:27], v[74:75], v[74:75], v[26:27]
	s_waitcnt vmcnt(9)
; #define LAS __attribute__((address_space(3)))
; __device__ __forceinline__ float bflo(unsigned w) { return __uint_as_float(w << 16); }
; __device__ __forceinline__ float bfhi(unsigned w) { return __uint_as_float(w & 0xffff0000u); }
; #define LAUNDER_ROW(pw, hw) do { LAUNDER8(pw, 0); LAUNDER8(pw, 8); LAUNDER8(hw, 0); LAUNDER8(hw, 8); } while (0)
; template <int MODE> ...
;     ...
;             const float ri = 1.f / rs[row];
; #pragma unroll
;             for (int j = 0; j < 16; ++j) { const float a = bflo(hw[j].x), b = bfhi(hw[j].x), c = bflo(hw[j].y), d = bfhi(hw[j].y); ss += a * a + b * b + c * c + d * d; }
;             const float rstd = rsqrtf(wave_sum(ss) * (1.f / DM) + EPS);
;             asm volatile("" ::: "memory");
;             LAUNDER_ROW(pw, hw);
;             float ss2 = 0.f;
; #pragma unroll
;             for (int j = 0; j < 16; ++j) { const f32x4 g = *(const LAS f32x4*)(GP + lo4 + 256 * j), gi = *(const LAS f32x4*)(GI + lo4 + 256 * j);
;                 f32x4 x;
;                 x.x = bflo(pw[j].x) * ri * gi.x + bflo(hw[j].x) * rstd * g.x; x.y = bfhi(pw[j].x) * ri * gi.y + bfhi(hw[j].x) * rstd * g.y;
;                 x.z = bflo(pw[j].y) * ri * gi.z + bflo(hw[j].y) * rstd * g.z; x.w = bfhi(pw[j].y) * ri * gi.w + bfhi(hw[j].y) * rstd * g.w;
;                 if (MODE == 2) *(f32x4*)(xout + (size_t)row * DM + lo4 + 256 * j) = x;
;                 else ss2 += x.x * x.x + x.y * x.y + x.z * x.z + x.w * x.w;
	v_and_b32_e32 v73, 0xffff0000, v4
	v_pk_fma_f32 v[26:27], v[76:77], v[76:77], v[26:27]
	v_and_b32_e32 v72, 0xffff0000, v8
	v_add_f32_e32 v26, v70, v26
	v_add_f32_e32 v70, v26, v27
	v_lshlrev_b32_e32 v27, 16, v4
	v_lshlrev_b32_e32 v26, 16, v8
	v_pk_mul_f32 v[72:73], v[72:73], v[72:73]
	v_lshlrev_b32_e32 v75, 16, v5
	v_lshlrev_b32_e32 v74, 16, v9
	v_pk_fma_f32 v[26:27], v[26:27], v[26:27], v[72:73]
	v_and_b32_e32 v77, 0xffff0000, v5
	v_and_b32_e32 v76, 0xffff0000, v9
	v_pk_fma_f32 v[26:27], v[74:75], v[74:75], v[26:27]
	s_waitcnt vmcnt(0)
	v_pk_fma_f32 v[26:27], v[76:77], v[76:77], v[26:27]
	v_div_scale_f32 v77, s[6:7], v78, v78, 1.0
	v_add_f32_e32 v26, v70, v26
	v_add_f32_e32 v26, v26, v27
	v_and_b32_e32 v27, 64, v101
	v_add_u32_e32 v27, 64, v27
	v_xor_b32_e32 v70, 1, v101
	v_cmp_lt_i32_e32 vcc, v70, v27
	v_rcp_f32_e32 v80, v77
	s_nop 0
	v_cndmask_b32_e32 v70, v101, v70, vcc
	v_lshlrev_b32_e32 v70, 2, v70
	ds_bpermute_b32 v72, v70, v26
	v_fma_f32 v81, -v77, v80, 1.0
	v_fmac_f32_e32 v80, v81, v80
	s_waitcnt lgkmcnt(0)
	v_add_f32_e32 v26, v26, v72
	v_xor_b32_e32 v72, 2, v101
	v_cmp_lt_i32_e32 vcc, v72, v27
	s_nop 1
	v_cndmask_b32_e32 v72, v101, v72, vcc
	v_lshlrev_b32_e32 v72, 2, v72
	ds_bpermute_b32 v73, v72, v26
	s_waitcnt lgkmcnt(0)
	v_add_f32_e32 v26, v26, v73
	v_xor_b32_e32 v73, 4, v101
	v_cmp_lt_i32_e32 vcc, v73, v27
	s_nop 1
	v_cndmask_b32_e32 v73, v101, v73, vcc
	v_lshlrev_b32_e32 v73, 2, v73
	ds_bpermute_b32 v74, v73, v26
	s_waitcnt lgkmcnt(0)
	v_add_f32_e32 v26, v26, v74
	v_xor_b32_e32 v74, 8, v101
	v_cmp_lt_i32_e32 vcc, v74, v27
	s_nop 1
	v_cndmask_b32_e32 v74, v101, v74, vcc
	v_lshlrev_b32_e32 v74, 2, v74
	ds_bpermute_b32 v75, v74, v26
	s_waitcnt lgkmcnt(0)
	v_add_f32_e32 v26, v26, v75
	v_xor_b32_e32 v75, 16, v101
	v_cmp_lt_i32_e32 vcc, v75, v27
	s_nop 1
	v_cndmask_b32_e32 v75, v101, v75, vcc
	v_lshlrev_b32_e32 v75, 2, v75
	ds_bpermute_b32 v76, v75, v26
	v_div_scale_f32 v81, vcc, 1.0, v78, 1.0
	v_mul_f32_e32 v82, v81, v80
	v_fma_f32 v83, -v77, v82, v81
	s_waitcnt lgkmcnt(0)
	v_add_f32_e32 v26, v26, v76
	v_xor_b32_e32 v76, 32, v101
	v_cmp_lt_i32_e64 s[6:7], v76, v27
	v_fmac_f32_e32 v82, v83, v80
	v_fma_f32 v77, -v77, v82, v81
	v_cndmask_b32_e64 v27, v101, v76, s[6:7]
	v_lshlrev_b32_e32 v76, 2, v27
	ds_bpermute_b32 v27, v76, v26
	s_waitcnt lgkmcnt(0)
	v_add_f32_e32 v26, v26, v27
	v_fmamk_f32 v26, v26, 0x39800000, v100
	v_mul_f32_e32 v27, 0x4b800000, v26
	v_cmp_gt_f32_e64 s[6:7], s66, v26
	s_nop 1
	v_cndmask_b32_e64 v26, v26, v27, s[6:7]
	v_rsq_f32_e32 v27, v26
	v_div_fmas_f32 v26, v77, v80, v82
	v_div_fixup_f32 v26, v26, v78, 1.0
	v_mul_f32_e32 v77, 0x45800000, v27
	v_cndmask_b32_e64 v27, v27, v77, s[6:7]
	v_mov_b32_e32 v228, v26
	v_mov_b32_e32 v229, v26
	v_mov_b32_e32 v230, v27
	v_mov_b32_e32 v231, v27
	ds_read_b128 v[196:199], v71
	ds_read_b128 v[200:203], v71 offset:32768
	ds_read_b128 v[204:207], v71 offset:1024
	ds_read_b128 v[208:211], v71 offset:33792
	v_lshlrev_b32_e32 v212, 16, v66
	v_and_b32_e32 v213, 0xffff0000, v66
	v_lshlrev_b32_e32 v214, 16, v67
	v_and_b32_e32 v215, 0xffff0000, v67
	v_lshlrev_b32_e32 v216, 16, v60
	v_and_b32_e32 v217, 0xffff0000, v60
	v_lshlrev_b32_e32 v218, 16, v61
	v_and_b32_e32 v219, 0xffff0000, v61
	v_pk_mul_f32 v[212:213], v[228:229], v[212:213]
	v_pk_mul_f32 v[214:215], v[228:229], v[214:215]
	v_pk_mul_f32 v[216:217], v[230:231], v[216:217]
	v_pk_mul_f32 v[218:219], v[230:231], v[218:219]
	s_waitcnt lgkmcnt(2)
	v_pk_mul_f32 v[132:133], v[212:213], v[200:201]
	v_pk_mul_f32 v[134:135], v[214:215], v[202:203]
	v_pk_fma_f32 v[132:133], v[196:197], v[216:217], v[132:133]
	v_pk_fma_f32 v[134:135], v[198:199], v[218:219], v[134:135]
	v_pk_mul_f32 v[234:235], v[132:133], v[132:133]
	v_pk_fma_f32 v[234:235], v[134:135], v[134:135], v[234:235]
	ds_read_b128 v[196:199], v71 offset:2048
	ds_read_b128 v[200:203], v71 offset:34816
	v_lshlrev_b32_e32 v212, 16, v64
	v_and_b32_e32 v213, 0xffff0000, v64
	v_lshlrev_b32_e32 v214, 16, v65
	v_and_b32_e32 v215, 0xffff0000, v65
	v_lshlrev_b32_e32 v216, 16, v56
	v_and_b32_e32 v217, 0xffff0000, v56
	v_lshlrev_b32_e32 v218, 16, v57
	v_and_b32_e32 v219, 0xffff0000, v57
	v_pk_mul_f32 v[212:213], v[228:229], v[212:213]
	v_pk_mul_f32 v[214:215], v[228:229], v[214:215]
	v_pk_mul_f32 v[216:217], v[230:231], v[216:217]
	v_pk_mul_f32 v[218:219], v[230:231], v[218:219]
	s_waitcnt lgkmcnt(2)
	v_pk_mul_f32 v[136:137], v[212:213], v[208:209]
	v_pk_mul_f32 v[138:139], v[214:215], v[210:211]
	v_pk_fma_f32 v[136:137], v[204:205], v[216:217], v[136:137]
	v_pk_fma_f32 v[138:139], v[206:207], v[218:219], v[138:139]
	v_pk_fma_f32 v[234:235], v[136:137], v[136:137], v[234:235]
	v_pk_fma_f32 v[234:235], v[138:139], v[138:139], v[234:235]
	ds_read_b128 v[204:207], v71 offset:3072
	ds_read_b128 v[208:211], v71 offset:35840
	v_lshlrev_b32_e32 v212, 16, v62
	v_and_b32_e32 v213, 0xffff0000, v62
	v_lshlrev_b32_e32 v214, 16, v63
	v_and_b32_e32 v215, 0xffff0000, v63
	v_lshlrev_b32_e32 v216, 16, v54
	v_and_b32_e32 v217, 0xffff0000, v54
	v_lshlrev_b32_e32 v218, 16, v55
	v_and_b32_e32 v219, 0xffff0000, v55
	v_pk_mul_f32 v[212:213], v[228:229], v[212:213]
	v_pk_mul_f32 v[214:215], v[228:229], v[214:215]
	v_pk_mul_f32 v[216:217], v[230:231], v[216:217]
	v_pk_mul_f32 v[218:219], v[230:231], v[218:219]
	s_waitcnt lgkmcnt(2)
; #define LAS __attribute__((address_space(3)))
; __device__ __forceinline__ float bflo(unsigned w) { return __uint_as_float(w << 16); }
; __device__ __forceinline__ float bfhi(unsigned w) { return __uint_as_float(w & 0xffff0000u); }
; template <int MODE> ...
;     ...
; #pragma unroll
;             for (int j = 0; j < 16; ++j) { const f32x4 g = *(const LAS f32x4*)(GP + lo4 + 256 * j), gi = *(const LAS f32x4*)(GI + lo4 + 256 * j);
;                 f32x4 x;
;                 x.x = bflo(pw[j].x) * ri * gi.x + bflo(hw[j].x) * rstd * g.x; x.y = bfhi(pw[j].x) * ri * gi.y + bfhi(hw[j].x) * rstd * g.y;
;                 x.z = bflo(pw[j].y) * ri * gi.z + bflo(hw[j].y) * rstd * g.z; x.w = bfhi(pw[j].y) * ri * gi.w + bfhi(hw[j].y) * rstd * g.w;
;                 if (MODE == 2) *(f32x4*)(xout + (size_t)row * DM + lo4 + 256 * j) = x;
;                 else ss2 += x.x * x.x + x.y * x.y + x.z * x.z + x.w * x.w;
;                 if (j & 1) __builtin_amdgcn_sched_barrier(0); }
	v_pk_mul_f32 v[140:141], v[212:213], v[200:201]
	v_pk_mul_f32 v[142:143], v[214:215], v[202:203]
	v_pk_fma_f32 v[140:141], v[196:197], v[216:217], v[140:141]
	v_pk_fma_f32 v[142:143], v[198:199], v[218:219], v[142:143]
	v_pk_fma_f32 v[234:235], v[140:141], v[140:141], v[234:235]
	v_pk_fma_f32 v[234:235], v[142:143], v[142:143], v[234:235]
	ds_read_b128 v[196:199], v71 offset:4096
	ds_read_b128 v[200:203], v71 offset:36864
	v_lshlrev_b32_e32 v212, 16, v58
	v_and_b32_e32 v213, 0xffff0000, v58
	v_lshlrev_b32_e32 v214, 16, v59
	v_and_b32_e32 v215, 0xffff0000, v59
	v_lshlrev_b32_e32 v216, 16, v50
	v_and_b32_e32 v217, 0xffff0000, v50
	v_lshlrev_b32_e32 v218, 16, v51
	v_and_b32_e32 v219, 0xffff0000, v51
	v_pk_mul_f32 v[212:213], v[228:229], v[212:213]
	v_pk_mul_f32 v[214:215], v[228:229], v[214:215]
	v_pk_mul_f32 v[216:217], v[230:231], v[216:217]
	v_pk_mul_f32 v[218:219], v[230:231], v[218:219]
	s_waitcnt lgkmcnt(2)
	v_pk_mul_f32 v[144:145], v[212:213], v[208:209]
	v_pk_mul_f32 v[146:147], v[214:215], v[210:211]
	v_pk_fma_f32 v[144:145], v[204:205], v[216:217], v[144:145]
	v_pk_fma_f32 v[146:147], v[206:207], v[218:219], v[146:147]
	v_pk_fma_f32 v[234:235], v[144:145], v[144:145], v[234:235]
	v_pk_fma_f32 v[234:235], v[146:147], v[146:147], v[234:235]
	ds_read_b128 v[204:207], v71 offset:5120
	ds_read_b128 v[208:211], v71 offset:37888
	v_lshlrev_b32_e32 v212, 16, v52
	v_and_b32_e32 v213, 0xffff0000, v52
	v_lshlrev_b32_e32 v214, 16, v53
	v_and_b32_e32 v215, 0xffff0000, v53
	v_lshlrev_b32_e32 v216, 16, v46
	v_and_b32_e32 v217, 0xffff0000, v46
	v_lshlrev_b32_e32 v218, 16, v47
	v_and_b32_e32 v219, 0xffff0000, v47
	v_pk_mul_f32 v[212:213], v[228:229], v[212:213]
	v_pk_mul_f32 v[214:215], v[228:229], v[214:215]
	v_pk_mul_f32 v[216:217], v[230:231], v[216:217]
	v_pk_mul_f32 v[218:219], v[230:231], v[218:219]
	s_waitcnt lgkmcnt(2)
	v_pk_mul_f32 v[148:149], v[212:213], v[200:201]
	v_pk_mul_f32 v[150:151], v[214:215], v[202:203]
	v_pk_fma_f32 v[148:149], v[196:197], v[216:217], v[148:149]
	v_pk_fma_f32 v[150:151], v[198:199], v[218:219], v[150:151]
	v_pk_fma_f32 v[234:235], v[148:149], v[148:149], v[234:235]
	v_pk_fma_f32 v[234:235], v[150:151], v[150:151], v[234:235]
	ds_read_b128 v[196:199], v71 offset:6144
	ds_read_b128 v[200:203], v71 offset:38912
	v_lshlrev_b32_e32 v212, 16, v48
	v_and_b32_e32 v213, 0xffff0000, v48
	v_lshlrev_b32_e32 v214, 16, v49
	v_and_b32_e32 v215, 0xffff0000, v49
	v_lshlrev_b32_e32 v216, 16, v44
	v_and_b32_e32 v217, 0xffff0000, v44
	v_lshlrev_b32_e32 v218, 16, v45
	v_and_b32_e32 v219, 0xffff0000, v45
	v_pk_mul_f32 v[212:213], v[228:229], v[212:213]
	v_pk_mul_f32 v[214:215], v[228:229], v[214:215]
	v_pk_mul_f32 v[216:217], v[230:231], v[216:217]
	v_pk_mul_f32 v[218:219], v[230:231], v[218:219]
	s_waitcnt lgkmcnt(2)
	v_pk_mul_f32 v[152:153], v[212:213], v[208:209]
	v_pk_mul_f32 v[154:155], v[214:215], v[210:211]
	v_pk_fma_f32 v[152:153], v[204:205], v[216:217], v[152:153]
	v_pk_fma_f32 v[154:155], v[206:207], v[218:219], v[154:155]
	v_pk_fma_f32 v[234:235], v[152:153], v[152:153], v[234:235]
	v_pk_fma_f32 v[234:235], v[154:155], v[154:155], v[234:235]
	ds_read_b128 v[204:207], v71 offset:7168
	ds_read_b128 v[208:211], v71 offset:39936
	v_lshlrev_b32_e32 v212, 16, v42
	v_and_b32_e32 v213, 0xffff0000, v42
	v_lshlrev_b32_e32 v214, 16, v43
	v_and_b32_e32 v215, 0xffff0000, v43
	v_lshlrev_b32_e32 v216, 16, v40
	v_and_b32_e32 v217, 0xffff0000, v40
	v_lshlrev_b32_e32 v218, 16, v41
	v_and_b32_e32 v219, 0xffff0000, v41
	v_pk_mul_f32 v[212:213], v[228:229], v[212:213]
	v_pk_mul_f32 v[214:215], v[228:229], v[214:215]
	v_pk_mul_f32 v[216:217], v[230:231], v[216:217]
	v_pk_mul_f32 v[218:219], v[230:231], v[218:219]
	s_waitcnt lgkmcnt(2)
	v_pk_mul_f32 v[156:157], v[212:213], v[200:201]
	v_pk_mul_f32 v[158:159], v[214:215], v[202:203]
	v_pk_fma_f32 v[156:157], v[196:197], v[216:217], v[156:157]
	v_pk_fma_f32 v[158:159], v[198:199], v[218:219], v[158:159]
	v_pk_fma_f32 v[234:235], v[156:157], v[156:157], v[234:235]
	v_pk_fma_f32 v[234:235], v[158:159], v[158:159], v[234:235]
	ds_read_b128 v[196:199], v71 offset:8192
	ds_read_b128 v[200:203], v71 offset:40960
	v_lshlrev_b32_e32 v212, 16, v38
	v_and_b32_e32 v213, 0xffff0000, v38
	v_lshlrev_b32_e32 v214, 16, v39
	v_and_b32_e32 v215, 0xffff0000, v39
	v_lshlrev_b32_e32 v216, 16, v36
	v_and_b32_e32 v217, 0xffff0000, v36
	v_lshlrev_b32_e32 v218, 16, v37
	v_and_b32_e32 v219, 0xffff0000, v37
	v_pk_mul_f32 v[212:213], v[228:229], v[212:213]
	v_pk_mul_f32 v[214:215], v[228:229], v[214:215]
	v_pk_mul_f32 v[216:217], v[230:231], v[216:217]
	v_pk_mul_f32 v[218:219], v[230:231], v[218:219]
	s_waitcnt lgkmcnt(2)
	v_pk_mul_f32 v[160:161], v[212:213], v[208:209]
	v_pk_mul_f32 v[162:163], v[214:215], v[210:211]
	v_pk_fma_f32 v[160:161], v[204:205], v[216:217], v[160:161]
	v_pk_fma_f32 v[162:163], v[206:207], v[218:219], v[162:163]
	v_pk_fma_f32 v[234:235], v[160:161], v[160:161], v[234:235]
	v_pk_fma_f32 v[234:235], v[162:163], v[162:163], v[234:235]
	ds_read_b128 v[204:207], v71 offset:9216
	ds_read_b128 v[208:211], v71 offset:41984
	v_lshlrev_b32_e32 v212, 16, v32
	v_and_b32_e32 v213, 0xffff0000, v32
	v_lshlrev_b32_e32 v214, 16, v33
	v_and_b32_e32 v215, 0xffff0000, v33
	v_lshlrev_b32_e32 v216, 16, v34
	v_and_b32_e32 v217, 0xffff0000, v34
	v_lshlrev_b32_e32 v218, 16, v35
	v_and_b32_e32 v219, 0xffff0000, v35
	v_pk_mul_f32 v[212:213], v[228:229], v[212:213]
	v_pk_mul_f32 v[214:215], v[228:229], v[214:215]
	v_pk_mul_f32 v[216:217], v[230:231], v[216:217]
	v_pk_mul_f32 v[218:219], v[230:231], v[218:219]
	s_waitcnt lgkmcnt(2)
; #define LAS __attribute__((address_space(3)))
; __device__ __forceinline__ float bflo(unsigned w) { return __uint_as_float(w << 16); }
; __device__ __forceinline__ float bfhi(unsigned w) { return __uint_as_float(w & 0xffff0000u); }
; template <int MODE> ...
;     ...
; #pragma unroll
;             for (int j = 0; j < 16; ++j) { const f32x4 g = *(const LAS f32x4*)(GP + lo4 + 256 * j), gi = *(const LAS f32x4*)(GI + lo4 + 256 * j);
;                 f32x4 x;
;                 x.x = bflo(pw[j].x) * ri * gi.x + bflo(hw[j].x) * rstd * g.x; x.y = bfhi(pw[j].x) * ri * gi.y + bfhi(hw[j].x) * rstd * g.y;
;                 x.z = bflo(pw[j].y) * ri * gi.z + bflo(hw[j].y) * rstd * g.z; x.w = bfhi(pw[j].y) * ri * gi.w + bfhi(hw[j].y) * rstd * g.w;
;                 if (MODE == 2) *(f32x4*)(xout + (size_t)row * DM + lo4 + 256 * j) = x;
;                 else ss2 += x.x * x.x + x.y * x.y + x.z * x.z + x.w * x.w;
;                 if (j & 1) __builtin_amdgcn_sched_barrier(0); }
	v_pk_mul_f32 v[164:165], v[212:213], v[200:201]
	v_pk_mul_f32 v[166:167], v[214:215], v[202:203]
	v_pk_fma_f32 v[164:165], v[196:197], v[216:217], v[164:165]
	v_pk_fma_f32 v[166:167], v[198:199], v[218:219], v[166:167]
	v_pk_fma_f32 v[234:235], v[164:165], v[164:165], v[234:235]
	v_pk_fma_f32 v[234:235], v[166:167], v[166:167], v[234:235]
	ds_read_b128 v[196:199], v71 offset:10240
	ds_read_b128 v[200:203], v71 offset:43008
	v_lshlrev_b32_e32 v212, 16, v28
	v_and_b32_e32 v213, 0xffff0000, v28
	v_lshlrev_b32_e32 v214, 16, v29
	v_and_b32_e32 v215, 0xffff0000, v29
	v_lshlrev_b32_e32 v216, 16, v30
	v_and_b32_e32 v217, 0xffff0000, v30
	v_lshlrev_b32_e32 v218, 16, v31
	v_and_b32_e32 v219, 0xffff0000, v31
	v_pk_mul_f32 v[212:213], v[228:229], v[212:213]
	v_pk_mul_f32 v[214:215], v[228:229], v[214:215]
	v_pk_mul_f32 v[216:217], v[230:231], v[216:217]
	v_pk_mul_f32 v[218:219], v[230:231], v[218:219]
	s_waitcnt lgkmcnt(2)
	v_pk_mul_f32 v[168:169], v[212:213], v[208:209]
	v_pk_mul_f32 v[170:171], v[214:215], v[210:211]
	v_pk_fma_f32 v[168:169], v[204:205], v[216:217], v[168:169]
	v_pk_fma_f32 v[170:171], v[206:207], v[218:219], v[170:171]
	v_pk_fma_f32 v[234:235], v[168:169], v[168:169], v[234:235]
	v_pk_fma_f32 v[234:235], v[170:171], v[170:171], v[234:235]
	ds_read_b128 v[204:207], v71 offset:11264
	ds_read_b128 v[208:211], v71 offset:44032
	v_lshlrev_b32_e32 v212, 16, v22
	v_and_b32_e32 v213, 0xffff0000, v22
	v_lshlrev_b32_e32 v214, 16, v23
	v_and_b32_e32 v215, 0xffff0000, v23
	v_lshlrev_b32_e32 v216, 16, v24
	v_and_b32_e32 v217, 0xffff0000, v24
	v_lshlrev_b32_e32 v218, 16, v25
	v_and_b32_e32 v219, 0xffff0000, v25
	v_pk_mul_f32 v[212:213], v[228:229], v[212:213]
	v_pk_mul_f32 v[214:215], v[228:229], v[214:215]
	v_pk_mul_f32 v[216:217], v[230:231], v[216:217]
	v_pk_mul_f32 v[218:219], v[230:231], v[218:219]
	s_waitcnt lgkmcnt(2)
	v_pk_mul_f32 v[172:173], v[212:213], v[200:201]
	v_pk_mul_f32 v[174:175], v[214:215], v[202:203]
	v_pk_fma_f32 v[172:173], v[196:197], v[216:217], v[172:173]
	v_pk_fma_f32 v[174:175], v[198:199], v[218:219], v[174:175]
	v_pk_fma_f32 v[234:235], v[172:173], v[172:173], v[234:235]
	v_pk_fma_f32 v[234:235], v[174:175], v[174:175], v[234:235]
	ds_read_b128 v[196:199], v71 offset:12288
	ds_read_b128 v[200:203], v71 offset:45056
	v_lshlrev_b32_e32 v212, 16, v18
	v_and_b32_e32 v213, 0xffff0000, v18
	v_lshlrev_b32_e32 v214, 16, v19
	v_and_b32_e32 v215, 0xffff0000, v19
	v_lshlrev_b32_e32 v216, 16, v20
	v_and_b32_e32 v217, 0xffff0000, v20
	v_lshlrev_b32_e32 v218, 16, v21
	v_and_b32_e32 v219, 0xffff0000, v21
	v_pk_mul_f32 v[212:213], v[228:229], v[212:213]
	v_pk_mul_f32 v[214:215], v[228:229], v[214:215]
	v_pk_mul_f32 v[216:217], v[230:231], v[216:217]
	v_pk_mul_f32 v[218:219], v[230:231], v[218:219]
	s_waitcnt lgkmcnt(2)
	v_pk_mul_f32 v[176:177], v[212:213], v[208:209]
	v_pk_mul_f32 v[178:179], v[214:215], v[210:211]
	v_pk_fma_f32 v[176:177], v[204:205], v[216:217], v[176:177]
	v_pk_fma_f32 v[178:179], v[206:207], v[218:219], v[178:179]
	v_pk_fma_f32 v[234:235], v[176:177], v[176:177], v[234:235]
	v_pk_fma_f32 v[234:235], v[178:179], v[178:179], v[234:235]
	ds_read_b128 v[204:207], v71 offset:13312
	ds_read_b128 v[208:211], v71 offset:46080
	v_lshlrev_b32_e32 v212, 16, v14
	v_and_b32_e32 v213, 0xffff0000, v14
	v_lshlrev_b32_e32 v214, 16, v15
	v_and_b32_e32 v215, 0xffff0000, v15
	v_lshlrev_b32_e32 v216, 16, v16
	v_and_b32_e32 v217, 0xffff0000, v16
	v_lshlrev_b32_e32 v218, 16, v17
	v_and_b32_e32 v219, 0xffff0000, v17
	v_pk_mul_f32 v[212:213], v[228:229], v[212:213]
	v_pk_mul_f32 v[214:215], v[228:229], v[214:215]
	v_pk_mul_f32 v[216:217], v[230:231], v[216:217]
	v_pk_mul_f32 v[218:219], v[230:231], v[218:219]
	s_waitcnt lgkmcnt(2)
; #define LAS __attribute__((address_space(3)))
; __device__ __forceinline__ float bflo(unsigned w) { return __uint_as_float(w << 16); }
; __device__ __forceinline__ float bfhi(unsigned w) { return __uint_as_float(w & 0xffff0000u); }
; template <int MODE> ...
;     ...
; #pragma unroll
;             for (int j = 0; j < 16; ++j) { const f32x4 g = *(const LAS f32x4*)(GP + lo4 + 256 * j), gi = *(const LAS f32x4*)(GI + lo4 + 256 * j);
;                 f32x4 x;
;                 x.x = bflo(pw[j].x) * ri * gi.x + bflo(hw[j].x) * rstd * g.x; x.y = bfhi(pw[j].x) * ri * gi.y + bfhi(hw[j].x) * rstd * g.y;
;                 x.z = bflo(pw[j].y) * ri * gi.z + bflo(hw[j].y) * rstd * g.z; x.w = bfhi(pw[j].y) * ri * gi.w + bfhi(hw[j].y) * rstd * g.w;
;                 if (MODE == 2) *(f32x4*)(xout + (size_t)row * DM + lo4 + 256 * j) = x;
;                 else ss2 += x.x * x.x + x.y * x.y + x.z * x.z + x.w * x.w;
;                 if (j & 1) __builtin_amdgcn_sched_barrier(0); }
;             if (MODE == 1) {
;                 const float rstd2 = rsqrtf(wave_sum(ss2) * (1.f / DM) + EPS);
;                 if (lane == 0) rs_out[row] = rstd2;
	v_pk_mul_f32 v[180:181], v[212:213], v[200:201]
	v_pk_mul_f32 v[182:183], v[214:215], v[202:203]
	v_pk_fma_f32 v[180:181], v[196:197], v[216:217], v[180:181]
	v_pk_fma_f32 v[182:183], v[198:199], v[218:219], v[182:183]
	v_pk_fma_f32 v[234:235], v[180:181], v[180:181], v[234:235]
	v_pk_fma_f32 v[234:235], v[182:183], v[182:183], v[234:235]
	ds_read_b128 v[196:199], v71 offset:14336
	ds_read_b128 v[200:203], v71 offset:47104
	v_lshlrev_b32_e32 v212, 16, v10
	v_and_b32_e32 v213, 0xffff0000, v10
	v_lshlrev_b32_e32 v214, 16, v11
	v_and_b32_e32 v215, 0xffff0000, v11
	v_lshlrev_b32_e32 v216, 16, v12
	v_and_b32_e32 v217, 0xffff0000, v12
	v_lshlrev_b32_e32 v218, 16, v13
	v_and_b32_e32 v219, 0xffff0000, v13
	v_pk_mul_f32 v[212:213], v[228:229], v[212:213]
	v_pk_mul_f32 v[214:215], v[228:229], v[214:215]
	v_pk_mul_f32 v[216:217], v[230:231], v[216:217]
	v_pk_mul_f32 v[218:219], v[230:231], v[218:219]
	s_waitcnt lgkmcnt(2)
	v_pk_mul_f32 v[184:185], v[212:213], v[208:209]
	v_pk_mul_f32 v[186:187], v[214:215], v[210:211]
	v_pk_fma_f32 v[184:185], v[204:205], v[216:217], v[184:185]
	v_pk_fma_f32 v[186:187], v[206:207], v[218:219], v[186:187]
	v_pk_fma_f32 v[234:235], v[184:185], v[184:185], v[234:235]
	v_pk_fma_f32 v[234:235], v[186:187], v[186:187], v[234:235]
	ds_read_b128 v[204:207], v71 offset:15360
	ds_read_b128 v[208:211], v71 offset:48128
	v_lshlrev_b32_e32 v212, 16, v6
	v_and_b32_e32 v213, 0xffff0000, v6
	v_lshlrev_b32_e32 v214, 16, v7
	v_and_b32_e32 v215, 0xffff0000, v7
	v_lshlrev_b32_e32 v216, 16, v8
	v_and_b32_e32 v217, 0xffff0000, v8
	v_lshlrev_b32_e32 v218, 16, v9
	v_and_b32_e32 v219, 0xffff0000, v9
	v_pk_mul_f32 v[212:213], v[228:229], v[212:213]
	v_pk_mul_f32 v[214:215], v[228:229], v[214:215]
	v_pk_mul_f32 v[216:217], v[230:231], v[216:217]
	v_pk_mul_f32 v[218:219], v[230:231], v[218:219]
	s_waitcnt lgkmcnt(2)
	v_pk_mul_f32 v[188:189], v[212:213], v[200:201]
	v_pk_mul_f32 v[190:191], v[214:215], v[202:203]
	v_pk_fma_f32 v[188:189], v[196:197], v[216:217], v[188:189]
	v_pk_fma_f32 v[190:191], v[198:199], v[218:219], v[190:191]
	v_pk_fma_f32 v[234:235], v[188:189], v[188:189], v[234:235]
	v_pk_fma_f32 v[234:235], v[190:191], v[190:191], v[234:235]
	v_lshlrev_b32_e32 v212, 16, v2
	v_and_b32_e32 v213, 0xffff0000, v2
	v_lshlrev_b32_e32 v214, 16, v3
	v_and_b32_e32 v215, 0xffff0000, v3
	v_lshlrev_b32_e32 v216, 16, v4
	v_and_b32_e32 v217, 0xffff0000, v4
	v_lshlrev_b32_e32 v218, 16, v5
	v_and_b32_e32 v219, 0xffff0000, v5
	v_pk_mul_f32 v[212:213], v[228:229], v[212:213]
	v_pk_mul_f32 v[214:215], v[228:229], v[214:215]
	v_pk_mul_f32 v[216:217], v[230:231], v[216:217]
	v_pk_mul_f32 v[218:219], v[230:231], v[218:219]
	s_waitcnt lgkmcnt(0)
	v_pk_mul_f32 v[192:193], v[212:213], v[208:209]
	v_pk_mul_f32 v[194:195], v[214:215], v[210:211]
	v_pk_fma_f32 v[192:193], v[204:205], v[216:217], v[192:193]
	v_pk_fma_f32 v[194:195], v[206:207], v[218:219], v[194:195]
	v_pk_fma_f32 v[234:235], v[192:193], v[192:193], v[234:235]
	v_pk_fma_f32 v[234:235], v[194:195], v[194:195], v[234:235]
	v_add_f32_e32 v77, v234, v235
	ds_bpermute_b32 v70, v70, v77
	s_waitcnt lgkmcnt(0)
	v_add_f32_e32 v70, v77, v70
	ds_bpermute_b32 v72, v72, v70
	s_waitcnt lgkmcnt(0)
	v_add_f32_e32 v70, v70, v72
	ds_bpermute_b32 v72, v73, v70
	s_waitcnt lgkmcnt(0)
	v_add_f32_e32 v70, v70, v72
	ds_bpermute_b32 v72, v74, v70
	s_waitcnt lgkmcnt(0)
	v_add_f32_e32 v70, v70, v72
	ds_bpermute_b32 v72, v75, v70
	s_waitcnt lgkmcnt(0)
	v_add_f32_e32 v70, v70, v72
	ds_bpermute_b32 v72, v76, v70
	s_waitcnt lgkmcnt(0)
	v_add_f32_e32 v70, v70, v72
	v_fmamk_f32 v70, v70, 0x39800000, v100
	v_mul_f32_e32 v72, 0x4b800000, v70
	v_cmp_gt_f32_e32 vcc, s66, v70
	s_nop 1
	v_cndmask_b32_e32 v70, v70, v72, vcc
	v_rsq_f32_e32 v70, v70
	s_nop 0
	v_mul_f32_e32 v72, 0x45800000, v70
	v_cndmask_b32_e32 v70, v70, v72, vcc
	s_and_saveexec_b64 s[6:7], s[4:5]
	s_cbranch_execz .LBB0_1118
	global_store_dword v79, v70, s[62:63]
	s_branch .LBB0_1118

; #define LAS __attribute__((address_space(3)))
; template <int MODE> ...
;     ...
;     LAS float* GP = (LAS float*)lds; LAS float* GN = (LAS float*)(lds + 16384); LAS float* GI = (LAS float*)(lds + 32768);
;     __syncthreads();
; #pragma unroll
;     for (int i = 0; i < 2; ++i) { const int o = 4 * (tid + NTHREADS * i);
;         if (MODE != 0) { *(LAS f32x4*)(GP + o) = *(const f32x4*)(gpost + o); const f32x4 g = *(const f32x4*)(gprev + o); *(LAS f32x4*)(GI + o) = (f32x4){1.f / g.x, 1.f / g.y, 1.f / g.z, 1.f / g.w}; }
;         if (MODE != 2) *(LAS f32x4*)(GN + o) = *(const f32x4*)(gpre + o); }
;     __syncthreads();
;     const int lo4 = 4 * lane;
; #pragma unroll 1
;     for (int row = gw; row < SEQ; row += NGW) {
.LBB0_1610:
	s_cmp_gt_i32 s36, 14
	s_cselect_b64 s[6:7], -1, 0
	s_xor_b64 s[4:5], s[4:5], -1
	s_or_b64 s[4:5], s[6:7], s[4:5]
	s_and_b64 vcc, exec, s[4:5]
	s_cbranch_vccnz .LBB0_1616
	s_mov_b64 s[12:13], 0
	s_waitcnt vmcnt(0)
	v_mbcnt_lo_u32_b32 v2, -1, 0
	v_mbcnt_hi_u32_b32 v2, -1, v2
	s_load_dwordx4 s[4:7], s[0:1], 0xa8
	s_load_dwordx2 s[8:9], s[0:1], 0x10
	v_lshlrev_b32_e32 v0, 2, v2
	v_lshl_add_u32 v24, s89, 8, v0
	v_ashrrev_i32_e32 v25, 31, v24
	v_lshlrev_b64 v[20:21], 2, v[24:25]
	v_add_u32_e32 v12, 0x800, v24
	s_waitcnt lgkmcnt(0)
	v_lshl_add_u64 v[8:9], s[4:5], 0, v[20:21]
	v_ashrrev_i32_e32 v13, 31, v12
	s_barrier
	v_lshl_add_u64 v[4:5], s[6:7], 0, v[20:21]
	global_load_dwordx4 v[8:11], v[8:9], off
	v_lshlrev_b64 v[26:27], 2, v[12:13]
	global_load_dwordx4 v[4:7], v[4:5], off
	v_lshl_add_u64 v[12:13], s[6:7], 0, v[26:27]
	v_lshl_add_u64 v[16:17], s[4:5], 0, v[26:27]
	global_load_dwordx4 v[12:15], v[12:13], off
	s_add_u32 s4, s8, 0x4000
	global_load_dwordx4 v[16:19], v[16:17], off
	s_addc_u32 s5, s9, 0
	v_lshl_add_u64 v[20:21], s[4:5], 0, v[20:21]
	global_load_dwordx4 v[20:23], v[20:21], off
	v_lshl_add_u32 v1, v24, 2, 0
	v_lshl_add_u64 v[24:25], s[4:5], 0, v[26:27]
	global_load_dwordx4 v[24:27], v[24:25], off
	s_cmpk_gt_i32 s40, 0x1fff
	s_waitcnt vmcnt(5)
	v_div_scale_f32 v3, s[4:5], v8, v8, 1.0
	s_waitcnt vmcnt(4)
	ds_write_b128 v1, v[4:7]
	v_div_scale_f32 v5, s[4:5], v9, v9, 1.0
	v_rcp_f32_e32 v31, v3
	v_div_scale_f32 v7, s[6:7], v10, v10, 1.0
	v_rcp_f32_e32 v32, v5
	s_waitcnt vmcnt(3)
	ds_write_b128 v1, v[12:15] offset:8192
	s_waitcnt vmcnt(2)
	v_div_scale_f32 v12, s[10:11], v16, v16, 1.0
	v_div_scale_f32 v29, s[8:9], v11, v11, 1.0
	v_rcp_f32_e32 v33, v7
	v_rcp_f32_e32 v15, v12
	v_rcp_f32_e32 v34, v29
	s_waitcnt vmcnt(1)
	ds_write_b128 v1, v[20:23] offset:16384
	v_fma_f32 v21, -v3, v31, 1.0
	v_div_scale_f32 v4, vcc, 1.0, v8, 1.0
	v_fma_f32 v22, -v5, v32, 1.0
	v_fmac_f32_e32 v31, v21, v31
	v_div_scale_f32 v6, s[4:5], 1.0, v9, 1.0
	v_fma_f32 v23, -v7, v33, 1.0
	v_fmac_f32_e32 v32, v22, v32
	v_fma_f32 v21, -v12, v15, 1.0
	v_mul_f32_e32 v22, v4, v31
	v_div_scale_f32 v28, s[6:7], 1.0, v10, 1.0
	v_fma_f32 v35, -v29, v34, 1.0
	v_fmac_f32_e32 v33, v23, v33
	v_mul_f32_e32 v23, v6, v32
	v_fmac_f32_e32 v15, v21, v15
	v_fma_f32 v21, -v3, v22, v4
	v_div_scale_f32 v30, s[8:9], 1.0, v11, 1.0
	v_fmac_f32_e32 v34, v35, v34
	v_mul_f32_e32 v35, v28, v33
	v_fma_f32 v37, -v5, v23, v6
	v_fmac_f32_e32 v22, v21, v31
	v_div_scale_f32 v13, s[10:11], 1.0, v16, 1.0
	v_mul_f32_e32 v36, v30, v34
	v_fma_f32 v38, -v7, v35, v28
	v_fmac_f32_e32 v23, v37, v32
	v_fma_f32 v3, -v3, v22, v4
	v_div_scale_f32 v14, s[14:15], v17, v17, 1.0
	v_fma_f32 v39, -v29, v36, v30
	v_mul_f32_e32 v40, v13, v15
	v_fmac_f32_e32 v35, v38, v33
	v_fma_f32 v5, -v5, v23, v6
	v_div_fmas_f32 v3, v3, v31, v22
	s_mov_b64 vcc, s[4:5]
	v_rcp_f32_e32 v20, v14
	v_fmac_f32_e32 v36, v39, v34
	v_fma_f32 v21, -v12, v40, v13
	v_fma_f32 v6, -v7, v35, v28
	v_div_fixup_f32 v4, v3, v8, 1.0
	v_div_fmas_f32 v3, v5, v32, v23
	s_mov_b64 vcc, s[6:7]
	v_fma_f32 v7, -v29, v36, v30
	v_fmac_f32_e32 v40, v21, v15
	v_div_fixup_f32 v5, v3, v9, 1.0
	v_div_fmas_f32 v3, v6, v33, v35
	s_mov_b64 vcc, s[8:9]
	v_fma_f32 v12, -v12, v40, v13
	v_div_fixup_f32 v6, v3, v10, 1.0
	v_div_fmas_f32 v3, v7, v34, v36
	s_mov_b64 vcc, s[10:11]
	v_div_fixup_f32 v7, v3, v11, 1.0
	v_div_fmas_f32 v3, v12, v15, v40
	ds_write_b128 v1, v[4:7] offset:32768
	v_div_fixup_f32 v4, v3, v16, 1.0
	v_fma_f32 v3, -v14, v20, 1.0
	v_fmac_f32_e32 v20, v3, v20
	v_div_scale_f32 v3, vcc, 1.0, v17, 1.0
	v_mul_f32_e32 v5, v3, v20
	v_fma_f32 v6, -v14, v5, v3
	v_fmac_f32_e32 v5, v6, v20
	v_div_scale_f32 v6, s[4:5], v18, v18, 1.0
	v_rcp_f32_e32 v7, v6
	v_fma_f32 v3, -v14, v5, v3
	v_div_fmas_f32 v3, v3, v20, v5
	v_div_fixup_f32 v5, v3, v17, 1.0
	v_fma_f32 v3, -v6, v7, 1.0
	v_fmac_f32_e32 v7, v3, v7
	v_div_scale_f32 v3, vcc, 1.0, v18, 1.0
	v_mul_f32_e32 v8, v3, v7
	v_fma_f32 v9, -v6, v8, v3
	v_fmac_f32_e32 v8, v9, v7
	v_div_scale_f32 v9, s[4:5], v19, v19, 1.0
	v_rcp_f32_e32 v10, v9
	v_fma_f32 v3, -v6, v8, v3
	v_div_fmas_f32 v3, v3, v7, v8
	v_div_fixup_f32 v6, v3, v18, 1.0
	v_fma_f32 v3, -v9, v10, 1.0
	v_fmac_f32_e32 v10, v3, v10
	v_div_scale_f32 v3, vcc, 1.0, v19, 1.0
	v_mul_f32_e32 v7, v3, v10
	v_fma_f32 v8, -v9, v7, v3
	v_fmac_f32_e32 v7, v8, v10
	v_fma_f32 v3, -v9, v7, v3
	v_div_fmas_f32 v3, v3, v10, v7
	v_div_fixup_f32 v7, v3, v19, 1.0
	ds_write_b128 v1, v[4:7] offset:40960
	s_waitcnt vmcnt(0)
	ds_write_b128 v1, v[24:27] offset:24576
	s_waitcnt lgkmcnt(0)
	s_barrier
	s_cbranch_scc1 .LBB0_1616
	s_load_dwordx2 s[6:7], s[0:1], 0xe8
	s_ashr_i32 s41, s40, 31
	s_lshl_b64 s[8:9], s[40:41], 2
	v_ashrrev_i32_e32 v1, 31, v0
	v_cmp_eq_u32_e64 s[4:5], 0, v2
	s_waitcnt lgkmcnt(0)
	s_add_u32 s8, s6, s8
	s_addc_u32 s9, s7, s9
	s_add_u32 s64, s8, 0x2c0000
	s_addc_u32 s65, s9, 0
	s_ashr_i32 s39, s38, 31
	s_lshl_b64 s[8:9], s[38:39], 2
	s_lshl_b64 s[10:11], s[40:41], 13
	s_add_u32 s6, s6, s10
	s_addc_u32 s7, s7, s11
	v_mbcnt_lo_u32_b32 v2, -1, 0
	v_lshl_add_u32 v71, v0, 2, 0
	v_lshl_add_u64 v[0:1], v[0:1], 1, s[6:7]
	s_lshl_b64 s[10:11], s[38:39], 13
	s_mov_b64 s[14:15], 0x3000000
	s_mov_b64 s[18:19], 0x3000200
	s_mov_b64 s[20:21], 0x3000400
	s_mov_b64 s[22:23], 0x3000600
	s_mov_b64 s[24:25], 0x3000800
	s_mov_b64 s[26:27], 0x3000a00
	s_mov_b64 s[42:43], 0x3000c00
	s_mov_b64 s[44:45], 0x3000e00
	s_mov_b64 s[46:47], 0x3001000
	s_mov_b32 s39, 0x3001000
	s_mov_b32 s41, 0x7001000
	s_mov_b64 s[48:49], 0x3001200
	s_mov_b64 s[50:51], 0x3001400
	s_mov_b64 s[52:53], 0x3001600
	s_mov_b64 s[54:55], 0x3001800
	s_mov_b64 s[56:57], 0x3001a00
	s_mov_b64 s[58:59], 0x3001c00
	s_mov_b64 s[60:61], 0x3001e00
	v_mov_b32_e32 v98, 0
	v_mov_b32_e32 v99, 0x358637bd
	s_mov_b32 s66, 0x800000
	v_mbcnt_hi_u32_b32 v100, -1, v2
	s_mov_b32 s67, s40
	s_mov_b32 s96, 0x3000000
	s_mov_b32 s97, 0x3001000
	v_mbcnt_lo_u32_b32 v236, -1, 0
	v_mbcnt_hi_u32_b32 v236, -1, v236
	v_and_b32_e32 v236, 1, v236
	v_mul_u32_u24_e32 v236, 0x1f8, v236
	s_branch .LBB0_1614

; #define LAS __attribute__((address_space(3)))
; template <int MODE> ...
;     ...
;     LAS float* GP = (LAS float*)lds; LAS float* GN = (LAS float*)(lds + 16384); LAS float* GI = (LAS float*)(lds + 32768);
;     __syncthreads();
; #pragma unroll
;     for (int i = 0; i < 2; ++i) { const int o = 4 * (tid + NTHREADS * i);
;         if (MODE != 0) { *(LAS f32x4*)(GP + o) = *(const f32x4*)(gpost + o); const f32x4 g = *(const f32x4*)(gprev + o); *(LAS f32x4*)(GI + o) = (f32x4){1.f / g.x, 1.f / g.y, 1.f / g.z, 1.f / g.w}; }
;         if (MODE != 2) *(LAS f32x4*)(GN + o) = *(const f32x4*)(gpre + o); }
;     __syncthreads();
;     const int lo4 = 4 * lane;
; #pragma unroll 1
;     for (int row = gw; row < SEQ; row += NGW) {
.LBB0_1984:
	s_cmp_gt_i32 s36, 18
	s_cselect_b64 s[6:7], -1, 0
	s_xor_b64 s[4:5], s[4:5], -1
	s_or_b64 s[4:5], s[6:7], s[4:5]
	s_and_b64 vcc, exec, s[4:5]
	s_cbranch_vccnz .LBB0_1990
	s_mov_b64 s[12:13], 0
	s_waitcnt vmcnt(0)
	v_mbcnt_lo_u32_b32 v2, -1, 0
	v_mbcnt_hi_u32_b32 v2, -1, v2
	s_load_dwordx4 s[4:7], s[0:1], 0x10
	s_load_dwordx2 s[8:9], s[0:1], 0x70
	v_lshlrev_b32_e32 v0, 2, v2
	v_lshl_add_u32 v24, s89, 8, v0
	v_ashrrev_i32_e32 v25, 31, v24
	s_waitcnt lgkmcnt(0)
	s_add_u32 s4, s4, 0x4000
	s_addc_u32 s5, s5, 0
	v_lshlrev_b64 v[20:21], 2, v[24:25]
	v_lshl_add_u64 v[4:5], s[4:5], 0, v[20:21]
	v_add_u32_e32 v8, 0x800, v24
	s_barrier
	global_load_dwordx4 v[4:7], v[4:5], off
	v_ashrrev_i32_e32 v9, 31, v8
	v_lshlrev_b64 v[26:27], 2, v[8:9]
	v_lshl_add_u64 v[8:9], s[4:5], 0, v[26:27]
	s_add_u32 s4, s6, 0x4000
	s_addc_u32 s5, s7, 0
	s_add_u32 s6, s8, 0x4000
	v_lshl_add_u64 v[22:23], s[4:5], 0, v[20:21]
	global_load_dwordx4 v[8:11], v[8:9], off
	v_lshl_add_u64 v[28:29], s[4:5], 0, v[26:27]
	s_addc_u32 s7, s9, 0
	global_load_dwordx4 v[12:15], v[22:23], off
	global_load_dwordx4 v[16:19], v[28:29], off
	v_lshl_add_u64 v[20:21], s[6:7], 0, v[20:21]
	global_load_dwordx4 v[20:23], v[20:21], off
	v_lshl_add_u32 v1, v24, 2, 0
	v_lshl_add_u64 v[24:25], s[6:7], 0, v[26:27]
	global_load_dwordx4 v[24:27], v[24:25], off
	s_cmpk_gt_i32 s40, 0x1fff
	s_waitcnt vmcnt(3)
	ds_write_b128 v1, v[12:15]
	s_waitcnt vmcnt(2)
	ds_write_b128 v1, v[16:19] offset:8192
	s_waitcnt vmcnt(1)
	ds_write_b128 v1, v[20:23] offset:16384
	v_div_scale_f32 v3, s[4:5], v4, v4, 1.0
	v_div_scale_f32 v29, s[4:5], v5, v5, 1.0
	v_rcp_f32_e32 v37, v3
	v_div_scale_f32 v31, s[6:7], v6, v6, 1.0
	v_rcp_f32_e32 v38, v29
	v_div_scale_f32 v33, s[8:9], v7, v7, 1.0
	v_rcp_f32_e32 v39, v31
	v_rcp_f32_e32 v40, v33
	v_fma_f32 v12, -v3, v37, 1.0
	v_div_scale_f32 v28, vcc, 1.0, v4, 1.0
	v_fma_f32 v13, -v29, v38, 1.0
	v_fmac_f32_e32 v37, v12, v37
	v_div_scale_f32 v30, s[4:5], 1.0, v5, 1.0
	v_fma_f32 v14, -v31, v39, 1.0
	v_fmac_f32_e32 v38, v13, v38
	v_mul_f32_e32 v12, v28, v37
	v_div_scale_f32 v32, s[6:7], 1.0, v6, 1.0
	v_fma_f32 v15, -v33, v40, 1.0
	v_fmac_f32_e32 v39, v14, v39
	v_mul_f32_e32 v13, v30, v38
	v_fma_f32 v17, -v3, v12, v28
	v_div_scale_f32 v34, s[8:9], 1.0, v7, 1.0
	v_fmac_f32_e32 v40, v15, v40
	v_mul_f32_e32 v14, v32, v39
	v_fma_f32 v18, -v29, v13, v30
	v_fmac_f32_e32 v12, v17, v37
	v_div_scale_f32 v35, s[10:11], v8, v8, 1.0
	v_mul_f32_e32 v15, v34, v40
	v_fma_f32 v19, -v31, v14, v32
	v_fmac_f32_e32 v13, v18, v38
	v_fma_f32 v3, -v3, v12, v28
	v_rcp_f32_e32 v41, v35
	v_fma_f32 v20, -v33, v15, v34
	v_fmac_f32_e32 v14, v19, v39
	v_fma_f32 v17, -v29, v13, v30
	v_div_fmas_f32 v3, v3, v37, v12
	s_mov_b64 vcc, s[4:5]
	v_fmac_f32_e32 v15, v20, v40
	v_fma_f32 v18, -v31, v14, v32
	v_div_fixup_f32 v4, v3, v4, 1.0
	v_div_fmas_f32 v3, v17, v38, v13
	s_mov_b64 vcc, s[6:7]
	v_fma_f32 v19, -v33, v15, v34
	v_div_fixup_f32 v5, v3, v5, 1.0
	v_div_fmas_f32 v3, v18, v39, v14
	s_mov_b64 vcc, s[8:9]
	v_div_fixup_f32 v6, v3, v6, 1.0
	v_div_fmas_f32 v3, v19, v40, v15
	v_fma_f32 v16, -v35, v41, 1.0
	v_div_fixup_f32 v7, v3, v7, 1.0
	v_div_scale_f32 v3, s[4:5], v9, v9, 1.0
	v_div_scale_f32 v36, s[10:11], 1.0, v8, 1.0
	v_fmac_f32_e32 v41, v16, v41
	ds_write_b128 v1, v[4:7] offset:32768
	v_rcp_f32_e32 v5, v3
	v_mul_f32_e32 v16, v36, v41
	v_fma_f32 v21, -v35, v16, v36
	v_fmac_f32_e32 v16, v21, v41
	v_fma_f32 v20, -v35, v16, v36
	s_mov_b64 vcc, s[10:11]
	v_fma_f32 v6, -v3, v5, 1.0
	v_div_fmas_f32 v4, v20, v41, v16
	v_fmac_f32_e32 v5, v6, v5
	v_div_scale_f32 v6, vcc, 1.0, v9, 1.0
	v_mul_f32_e32 v7, v6, v5
	v_div_fixup_f32 v4, v4, v8, 1.0
	v_fma_f32 v8, -v3, v7, v6
	v_fmac_f32_e32 v7, v8, v5
	v_fma_f32 v3, -v3, v7, v6
	v_div_scale_f32 v6, s[4:5], v10, v10, 1.0
	v_rcp_f32_e32 v8, v6
	v_div_fmas_f32 v3, v3, v5, v7
	v_div_fixup_f32 v5, v3, v9, 1.0
	v_fma_f32 v3, -v6, v8, 1.0
	v_fmac_f32_e32 v8, v3, v8
	v_div_scale_f32 v3, vcc, 1.0, v10, 1.0
	v_mul_f32_e32 v7, v3, v8
	v_fma_f32 v9, -v6, v7, v3
	v_fmac_f32_e32 v7, v9, v8
	v_div_scale_f32 v9, s[4:5], v11, v11, 1.0
	v_rcp_f32_e32 v12, v9
	v_fma_f32 v3, -v6, v7, v3
	v_div_fmas_f32 v3, v3, v8, v7
	v_div_fixup_f32 v6, v3, v10, 1.0
	v_fma_f32 v3, -v9, v12, 1.0
	v_fmac_f32_e32 v12, v3, v12
	v_div_scale_f32 v3, vcc, 1.0, v11, 1.0
	v_mul_f32_e32 v7, v3, v12
	v_fma_f32 v8, -v9, v7, v3
	v_fmac_f32_e32 v7, v8, v12
	v_fma_f32 v3, -v9, v7, v3
	v_div_fmas_f32 v3, v3, v12, v7
	v_div_fixup_f32 v7, v3, v11, 1.0
	ds_write_b128 v1, v[4:7] offset:40960
	s_waitcnt vmcnt(0)
	ds_write_b128 v1, v[24:27] offset:24576
	s_waitcnt lgkmcnt(0)
	s_barrier
	s_cbranch_scc1 .LBB0_1990
	s_load_dwordx2 s[6:7], s[0:1], 0xe8
	s_ashr_i32 s41, s40, 31
	s_lshl_b64 s[8:9], s[40:41], 2
	v_ashrrev_i32_e32 v1, 31, v0
	v_cmp_eq_u32_e64 s[4:5], 0, v2
	s_waitcnt lgkmcnt(0)
	s_add_u32 s8, s6, s8
	s_addc_u32 s9, s7, s9
	s_add_u32 s64, s8, 0x2c0000
	s_addc_u32 s65, s9, 0
	s_ashr_i32 s39, s38, 31
	s_lshl_b64 s[8:9], s[38:39], 2
	s_lshl_b64 s[10:11], s[40:41], 13
	s_add_u32 s6, s6, s10
	s_addc_u32 s7, s7, s11
	v_mbcnt_lo_u32_b32 v2, -1, 0
	v_lshl_add_u32 v71, v0, 2, 0
	v_lshl_add_u64 v[0:1], v[0:1], 1, s[6:7]
	s_lshl_b64 s[10:11], s[38:39], 13
	s_mov_b64 s[14:15], 0x3000000
	s_mov_b64 s[18:19], 0x3000200
	s_mov_b64 s[20:21], 0x3000400
	s_mov_b64 s[22:23], 0x3000600
	s_mov_b64 s[24:25], 0x3000800
	s_mov_b64 s[26:27], 0x3000a00
	s_mov_b64 s[42:43], 0x3000c00
	s_mov_b64 s[44:45], 0x3000e00
	s_mov_b64 s[46:47], 0x3001000
	s_mov_b32 s39, 0x3001000
	s_mov_b32 s41, 0x7001000
	s_mov_b64 s[48:49], 0x3001200
	s_mov_b64 s[50:51], 0x3001400
	s_mov_b64 s[52:53], 0x3001600
	s_mov_b64 s[54:55], 0x3001800
	s_mov_b64 s[56:57], 0x3001a00
	s_mov_b64 s[58:59], 0x3001c00
	s_mov_b64 s[60:61], 0x3001e00
	v_mov_b32_e32 v79, 0
	v_mov_b32_e32 v100, 0x358637bd
	s_mov_b32 s66, 0x800000
	v_mbcnt_hi_u32_b32 v101, -1, v2
	s_mov_b32 s67, s40
	s_mov_b32 s96, 0x3000000
	s_mov_b32 s97, 0x3001000
	v_mbcnt_lo_u32_b32 v236, -1, 0
	v_mbcnt_hi_u32_b32 v236, -1, v236
	v_and_b32_e32 v236, 1, v236
	v_mul_u32_u24_e32 v236, 0x1f8, v236
	s_branch .LBB0_1988

; #define LAS __attribute__((address_space(3)))
; template <int MODE> ...
;     ...
;     LAS float* GP = (LAS float*)lds; LAS float* GN = (LAS float*)(lds + 16384); LAS float* GI = (LAS float*)(lds + 32768);
;     __syncthreads();
; #pragma unroll
;     for (int i = 0; i < 2; ++i) { const int o = 4 * (tid + NTHREADS * i);
;         if (MODE != 0) { *(LAS f32x4*)(GP + o) = *(const f32x4*)(gpost + o); const f32x4 g = *(const f32x4*)(gprev + o); *(LAS f32x4*)(GI + o) = (f32x4){1.f / g.x, 1.f / g.y, 1.f / g.z, 1.f / g.w}; }
;         if (MODE != 2) *(LAS f32x4*)(GN + o) = *(const f32x4*)(gpre + o); }
;     __syncthreads();
;     const int lo4 = 4 * lane;
; #pragma unroll 1
;     for (int row = gw; row < SEQ; row += NGW) {
.LBB0_2327:
	s_cmp_gt_i32 s36, 22
	s_cselect_b64 s[6:7], -1, 0
	s_xor_b64 s[4:5], s[4:5], -1
	s_or_b64 s[4:5], s[6:7], s[4:5]
	s_and_b64 vcc, exec, s[4:5]
	s_cbranch_vccnz .LBB0_2333
	s_mov_b64 s[12:13], 0
	s_waitcnt vmcnt(0)
	v_mbcnt_lo_u32_b32 v2, -1, 0
	v_mbcnt_hi_u32_b32 v2, -1, v2
	s_load_dwordx4 s[4:7], s[0:1], 0x70
	s_load_dwordx2 s[8:9], s[0:1], 0xa8
	v_lshlrev_b32_e32 v0, 2, v2
	v_lshl_add_u32 v24, s89, 8, v0
	v_ashrrev_i32_e32 v25, 31, v24
	s_waitcnt lgkmcnt(0)
	s_add_u32 s4, s4, 0x4000
	s_addc_u32 s5, s5, 0
	v_lshlrev_b64 v[20:21], 2, v[24:25]
	v_lshl_add_u64 v[4:5], s[4:5], 0, v[20:21]
	v_add_u32_e32 v8, 0x800, v24
	s_barrier
	global_load_dwordx4 v[4:7], v[4:5], off
	v_ashrrev_i32_e32 v9, 31, v8
	v_lshlrev_b64 v[26:27], 2, v[8:9]
	v_lshl_add_u64 v[8:9], s[4:5], 0, v[26:27]
	s_add_u32 s4, s6, 0x4000
	s_addc_u32 s5, s7, 0
	s_add_u32 s6, s8, 0x4000
	v_lshl_add_u64 v[22:23], s[4:5], 0, v[20:21]
	global_load_dwordx4 v[8:11], v[8:9], off
	v_lshl_add_u64 v[28:29], s[4:5], 0, v[26:27]
	s_addc_u32 s7, s9, 0
	global_load_dwordx4 v[12:15], v[22:23], off
	global_load_dwordx4 v[16:19], v[28:29], off
	v_lshl_add_u64 v[20:21], s[6:7], 0, v[20:21]
	global_load_dwordx4 v[20:23], v[20:21], off
	v_lshl_add_u32 v1, v24, 2, 0
	v_lshl_add_u64 v[24:25], s[6:7], 0, v[26:27]
	global_load_dwordx4 v[24:27], v[24:25], off
	s_cmpk_gt_i32 s40, 0x1fff
	s_waitcnt vmcnt(3)
	ds_write_b128 v1, v[12:15]
	s_waitcnt vmcnt(2)
	ds_write_b128 v1, v[16:19] offset:8192
	s_waitcnt vmcnt(1)
	ds_write_b128 v1, v[20:23] offset:16384
	v_div_scale_f32 v3, s[4:5], v4, v4, 1.0
	v_div_scale_f32 v29, s[4:5], v5, v5, 1.0
	v_rcp_f32_e32 v37, v3
	v_div_scale_f32 v31, s[6:7], v6, v6, 1.0
	v_rcp_f32_e32 v38, v29
	v_div_scale_f32 v33, s[8:9], v7, v7, 1.0
	v_rcp_f32_e32 v39, v31
	v_rcp_f32_e32 v40, v33
	v_fma_f32 v12, -v3, v37, 1.0
	v_div_scale_f32 v28, vcc, 1.0, v4, 1.0
	v_fma_f32 v13, -v29, v38, 1.0
	v_fmac_f32_e32 v37, v12, v37
	v_div_scale_f32 v30, s[4:5], 1.0, v5, 1.0
	v_fma_f32 v14, -v31, v39, 1.0
	v_fmac_f32_e32 v38, v13, v38
	v_mul_f32_e32 v12, v28, v37
	v_div_scale_f32 v32, s[6:7], 1.0, v6, 1.0
	v_fma_f32 v15, -v33, v40, 1.0
	v_fmac_f32_e32 v39, v14, v39
	v_mul_f32_e32 v13, v30, v38
	v_fma_f32 v17, -v3, v12, v28
	v_div_scale_f32 v34, s[8:9], 1.0, v7, 1.0
	v_fmac_f32_e32 v40, v15, v40
	v_mul_f32_e32 v14, v32, v39
	v_fma_f32 v18, -v29, v13, v30
	v_fmac_f32_e32 v12, v17, v37
	v_div_scale_f32 v35, s[10:11], v8, v8, 1.0
	v_mul_f32_e32 v15, v34, v40
	v_fma_f32 v19, -v31, v14, v32
	v_fmac_f32_e32 v13, v18, v38
	v_fma_f32 v3, -v3, v12, v28
	v_rcp_f32_e32 v41, v35
	v_fma_f32 v20, -v33, v15, v34
	v_fmac_f32_e32 v14, v19, v39
	v_fma_f32 v17, -v29, v13, v30
	v_div_fmas_f32 v3, v3, v37, v12
	s_mov_b64 vcc, s[4:5]
	v_fmac_f32_e32 v15, v20, v40
	v_fma_f32 v18, -v31, v14, v32
	v_div_fixup_f32 v4, v3, v4, 1.0
	v_div_fmas_f32 v3, v17, v38, v13
	s_mov_b64 vcc, s[6:7]
	v_fma_f32 v19, -v33, v15, v34
	v_div_fixup_f32 v5, v3, v5, 1.0
	v_div_fmas_f32 v3, v18, v39, v14
	s_mov_b64 vcc, s[8:9]
	v_div_fixup_f32 v6, v3, v6, 1.0
	v_div_fmas_f32 v3, v19, v40, v15
	v_fma_f32 v16, -v35, v41, 1.0
	v_div_fixup_f32 v7, v3, v7, 1.0
	v_div_scale_f32 v3, s[4:5], v9, v9, 1.0
	v_div_scale_f32 v36, s[10:11], 1.0, v8, 1.0
	v_fmac_f32_e32 v41, v16, v41
	ds_write_b128 v1, v[4:7] offset:32768
	v_rcp_f32_e32 v5, v3
	v_mul_f32_e32 v16, v36, v41
	v_fma_f32 v21, -v35, v16, v36
	v_fmac_f32_e32 v16, v21, v41
	v_fma_f32 v20, -v35, v16, v36
	s_mov_b64 vcc, s[10:11]
	v_fma_f32 v6, -v3, v5, 1.0
	v_div_fmas_f32 v4, v20, v41, v16
	v_fmac_f32_e32 v5, v6, v5
	v_div_scale_f32 v6, vcc, 1.0, v9, 1.0
	v_mul_f32_e32 v7, v6, v5
	v_div_fixup_f32 v4, v4, v8, 1.0
	v_fma_f32 v8, -v3, v7, v6
	v_fmac_f32_e32 v7, v8, v5
	v_fma_f32 v3, -v3, v7, v6
	v_div_scale_f32 v6, s[4:5], v10, v10, 1.0
	v_rcp_f32_e32 v8, v6
	v_div_fmas_f32 v3, v3, v5, v7
	v_div_fixup_f32 v5, v3, v9, 1.0
	v_fma_f32 v3, -v6, v8, 1.0
	v_fmac_f32_e32 v8, v3, v8
	v_div_scale_f32 v3, vcc, 1.0, v10, 1.0
	v_mul_f32_e32 v7, v3, v8
	v_fma_f32 v9, -v6, v7, v3
	v_fmac_f32_e32 v7, v9, v8
	v_div_scale_f32 v9, s[4:5], v11, v11, 1.0
	v_rcp_f32_e32 v12, v9
	v_fma_f32 v3, -v6, v7, v3
	v_div_fmas_f32 v3, v3, v8, v7
	v_div_fixup_f32 v6, v3, v10, 1.0
	v_fma_f32 v3, -v9, v12, 1.0
	v_fmac_f32_e32 v12, v3, v12
	v_div_scale_f32 v3, vcc, 1.0, v11, 1.0
	v_mul_f32_e32 v7, v3, v12
	v_fma_f32 v8, -v9, v7, v3
	v_fmac_f32_e32 v7, v8, v12
	v_fma_f32 v3, -v9, v7, v3
	v_div_fmas_f32 v3, v3, v12, v7
	v_div_fixup_f32 v7, v3, v11, 1.0
	ds_write_b128 v1, v[4:7] offset:40960
	s_waitcnt vmcnt(0)
	ds_write_b128 v1, v[24:27] offset:24576
	s_waitcnt lgkmcnt(0)
	s_barrier
	s_cbranch_scc1 .LBB0_2333
	s_load_dwordx2 s[6:7], s[0:1], 0xe8
	s_ashr_i32 s41, s40, 31
	s_lshl_b64 s[8:9], s[40:41], 2
	v_ashrrev_i32_e32 v1, 31, v0
	v_cmp_eq_u32_e64 s[4:5], 0, v2
	s_waitcnt lgkmcnt(0)
	s_add_u32 s8, s6, s8
	s_addc_u32 s9, s7, s9
	s_add_u32 s64, s8, 0x2c0000
	s_addc_u32 s65, s9, 0
	s_ashr_i32 s39, s38, 31
	s_lshl_b64 s[8:9], s[38:39], 2
	s_lshl_b64 s[10:11], s[40:41], 13
	s_add_u32 s6, s6, s10
	s_addc_u32 s7, s7, s11
	v_mbcnt_lo_u32_b32 v2, -1, 0
	v_lshl_add_u32 v71, v0, 2, 0
	v_lshl_add_u64 v[0:1], v[0:1], 1, s[6:7]
	s_lshl_b64 s[10:11], s[38:39], 13
	s_mov_b64 s[14:15], 0x3000000
	s_mov_b64 s[18:19], 0x3000200
	s_mov_b64 s[20:21], 0x3000400
	s_mov_b64 s[22:23], 0x3000600
	s_mov_b64 s[24:25], 0x3000800
	s_mov_b64 s[26:27], 0x3000a00
	s_mov_b64 s[42:43], 0x3000c00
	s_mov_b64 s[44:45], 0x3000e00
	s_mov_b64 s[46:47], 0x3001000
	s_mov_b32 s39, 0x3001000
	s_mov_b32 s41, 0x7001000
	s_mov_b64 s[48:49], 0x3001200
	s_mov_b64 s[50:51], 0x3001400
	s_mov_b64 s[52:53], 0x3001600
	s_mov_b64 s[54:55], 0x3001800
	s_mov_b64 s[56:57], 0x3001a00
	s_mov_b64 s[58:59], 0x3001c00
	s_mov_b64 s[60:61], 0x3001e00
	v_mov_b32_e32 v98, 0
	v_mov_b32_e32 v99, 0x358637bd
	s_mov_b32 s66, 0x800000
	v_mbcnt_hi_u32_b32 v100, -1, v2
	s_mov_b32 s67, s40
	s_mov_b32 s96, 0x3000000
	s_mov_b32 s97, 0x3001000
	v_mbcnt_lo_u32_b32 v236, -1, 0
	v_mbcnt_hi_u32_b32 v236, -1, v236
	v_and_b32_e32 v236, 1, v236
	v_mul_u32_u24_e32 v236, 0x1f8, v236
	s_branch .LBB0_2331
